# GEMM epilogues: global loads/stores switched from 64-bit vaddr to SGPR-base + 32-bit offset form (plus in-proj stagger)
# baseline (speedup 1.0000x reference)
.LBB0_460:
	v_lshl_add_u32 v140, s27, 8, v146
	v_lshrrev_b32_e32 v190, 4, v197
	v_and_b32_e32 v191, 1, v190
	v_lshlrev_b32_e32 v191, 5, v191
	v_lshrrev_b32_e32 v192, 1, v190
	v_lshl_add_u32 v191, v192, 7, v191
	v_add_u32_e32 v192, v140, v191
	v_ashrrev_i32_e32 v193, 31, v192
	v_lshlrev_b64 v[192:193], 6, v[192:193]
	v_lshl_add_u64 v[192:193], s[42:43], 0, v[192:193]
	v_subrev_u32_e32 v193, s40, v192
	global_load_dwordx4 v[172:175], v193, s[40:41]
	global_load_dwordx4 v[176:179], v193, s[40:41] offset:16
	global_load_dwordx4 v[180:183], v193, s[40:41] offset:32
	global_load_dwordx4 v[184:187], v193, s[40:41] offset:48
	global_load_dwordx4 v[226:229], v193, s[40:41] offset:1024
	global_load_dwordx4 v[230:233], v193, s[40:41] offset:1040
	global_load_dwordx4 v[234:237], v193, s[40:41] offset:1056
	global_load_dwordx4 v[238:241], v193, s[40:41] offset:1072
	s_waitcnt vmcnt(0)
	v_add_f32_e32 v172, v172, v173
	v_add_f32_e32 v174, v174, v175
	v_add_f32_e32 v172, v172, v174
	v_add_f32_e32 v176, v176, v177
	v_add_f32_e32 v178, v178, v179
	v_add_f32_e32 v176, v176, v178
	v_add_f32_e32 v180, v180, v181
	v_add_f32_e32 v182, v182, v183
	v_add_f32_e32 v180, v180, v182
	v_add_f32_e32 v184, v184, v185
	v_add_f32_e32 v186, v186, v187
	v_add_f32_e32 v184, v184, v186
	v_add_f32_e32 v172, v172, v176
	v_add_f32_e32 v180, v180, v184
	v_add_f32_e32 v188, v172, v180
	v_add_f32_e32 v226, v226, v227
	v_add_f32_e32 v228, v228, v229
	v_add_f32_e32 v226, v226, v228
	v_add_f32_e32 v230, v230, v231
	v_add_f32_e32 v232, v232, v233
	v_add_f32_e32 v230, v230, v232
	v_add_f32_e32 v234, v234, v235
	v_add_f32_e32 v236, v236, v237
	v_add_f32_e32 v234, v234, v236
	v_add_f32_e32 v238, v238, v239
	v_add_f32_e32 v240, v240, v241
	v_add_f32_e32 v238, v238, v240
	v_add_f32_e32 v226, v226, v230
	v_add_f32_e32 v234, v234, v238
	v_add_f32_e32 v189, v226, v234
	v_fmamk_f32 v188, v188, 0x3a800000, v194
	v_mul_f32_e32 v172, 0x4f800000, v188
	v_cmp_gt_f32_e32 vcc, 0xf800000, v188
	s_nop 1
	v_cndmask_b32_e32 v188, v188, v172, vcc
	v_sqrt_f32_e32 v172, v188
	s_nop 0
	v_add_u32_e32 v173, -1, v172
	v_add_u32_e32 v174, 1, v172
	v_fma_f32 v175, -v173, v172, v188
	v_cmp_ge_f32_e64 s[4:5], 0, v175
	v_fma_f32 v175, -v174, v172, v188
	s_nop 0
	v_cndmask_b32_e64 v172, v172, v173, s[4:5]
	v_cmp_lt_f32_e64 s[4:5], 0, v175
	s_nop 1
	v_cndmask_b32_e64 v172, v172, v174, s[4:5]
	v_mul_f32_e32 v173, 0x37800000, v172
	v_cndmask_b32_e32 v172, v172, v173, vcc
	v_cmp_class_f32_e32 vcc, v188, v195
	s_nop 1
	v_cndmask_b32_e32 v188, v172, v188, vcc
	v_div_scale_f32 v172, s[4:5], v188, v188, 1.0
	v_rcp_f32_e32 v173, v172
	v_div_scale_f32 v174, vcc, 1.0, v188, 1.0
	v_fma_f32 v175, -v172, v173, 1.0
	v_fmac_f32_e32 v173, v175, v173
	v_mul_f32_e32 v175, v174, v173
	v_fma_f32 v242, -v172, v175, v174
	v_fmac_f32_e32 v175, v242, v173
	v_fma_f32 v172, -v172, v175, v174
	v_div_fmas_f32 v172, v172, v173, v175
	v_div_fixup_f32 v188, v172, v188, 1.0
	v_fmamk_f32 v189, v189, 0x3a800000, v194
	v_mul_f32_e32 v176, 0x4f800000, v189
	v_cmp_gt_f32_e32 vcc, 0xf800000, v189
	s_nop 1
	v_cndmask_b32_e32 v189, v189, v176, vcc
	v_sqrt_f32_e32 v176, v189
	s_nop 0
	v_add_u32_e32 v177, -1, v176
	v_add_u32_e32 v178, 1, v176
	v_fma_f32 v179, -v177, v176, v189
	v_cmp_ge_f32_e64 s[4:5], 0, v179
	v_fma_f32 v179, -v178, v176, v189
	s_nop 0
	v_cndmask_b32_e64 v176, v176, v177, s[4:5]
	v_cmp_lt_f32_e64 s[4:5], 0, v179
	s_nop 1
	v_cndmask_b32_e64 v176, v176, v178, s[4:5]
	v_mul_f32_e32 v177, 0x37800000, v176
	v_cndmask_b32_e32 v176, v176, v177, vcc
	v_cmp_class_f32_e32 vcc, v189, v195
	s_nop 1
	v_cndmask_b32_e32 v189, v176, v189, vcc
	v_div_scale_f32 v176, s[4:5], v189, v189, 1.0
	v_rcp_f32_e32 v177, v176
	v_div_scale_f32 v178, vcc, 1.0, v189, 1.0
	v_fma_f32 v179, -v176, v177, 1.0
	v_fmac_f32_e32 v177, v179, v177
	v_mul_f32_e32 v179, v178, v177
	v_fma_f32 v242, -v176, v179, v178
	v_fmac_f32_e32 v179, v242, v177
	v_fma_f32 v176, -v176, v179, v178
	v_div_fmas_f32 v176, v176, v177, v179
	v_div_fixup_f32 v189, v176, v189, 1.0
	v_and_b32_e32 v190, 15, v197
	v_lshlrev_b32_e32 v190, 2, v190
	v_add_u32_e32 v191, 64, v190
	v_add_u32_e32 v192, 128, v190
	v_add_u32_e32 v193, 192, v190
	ds_bpermute_b32 v244, v190, v188
	ds_bpermute_b32 v245, v190, v189
	ds_bpermute_b32 v246, v191, v188
	ds_bpermute_b32 v247, v191, v189
	ds_bpermute_b32 v248, v192, v188
	ds_bpermute_b32 v249, v192, v189
	ds_bpermute_b32 v250, v193, v188
	ds_bpermute_b32 v251, v193, v189
	s_waitcnt lgkmcnt(0)
	v_ashrrev_i32_e32 v141, 31, v140
	v_lshlrev_b64 v[144:145], 6, v[140:141]
	v_lshl_add_u64 v[142:143], s[42:43], 0, v[144:145]
	s_mov_b32 s4, 0xf800000
	v_mov_b64_e32 v[164:165], s[36:37]
	v_lshl_or_b32 v142, s26, 8, v148
	s_movk_i32 s33, 0xac7
	s_waitcnt lgkmcnt(0)
	s_nop 0
	s_nop 0
	s_movk_i32 s4, 0x1600
	v_mad_i64_i32 v[150:151], s[4:5], v140, s4, v[164:165]
	v_ashrrev_i32_e32 v143, 31, v142
	v_lshl_add_u64 v[150:151], v[142:143], 1, v[150:151]
	v_subrev_u32_e32 v151, s40, v150
	s_nop 1
	s_nop 1
	s_nop 1
	s_mov_b64 s[4:5], 0
	v_mov_b32_e32 v152, v244
	v_pk_mul_f32 v[128:129], v[128:129], v[152:153] op_sel_hi:[1,0]
	v_pk_mul_f32 v[126:127], v[126:127], v[152:153] op_sel_hi:[1,0]
	v_pk_mul_f32 v[154:155], v[124:125], v[152:153] op_sel_hi:[1,0]
	v_pk_mul_f32 v[124:125], v[122:123], v[152:153] op_sel_hi:[1,0]
	v_pk_mul_f32 v[114:115], v[114:115], v[152:153] op_sel_hi:[1,0]
	v_pk_mul_f32 v[120:121], v[120:121], v[152:153] op_sel_hi:[1,0]
	v_pk_mul_f32 v[118:119], v[118:119], v[152:153] op_sel_hi:[1,0]
	v_pk_mul_f32 v[116:117], v[116:117], v[152:153] op_sel_hi:[1,0]
	v_cvt_pk_bf16_f32 v122, v126, v127
	v_cvt_pk_bf16_f32 v123, v128, v129
	v_cvt_pk_bf16_f32 v124, v124, v125
	v_cvt_pk_bf16_f32 v125, v154, v155
	v_cvt_pk_bf16_f32 v128, v114, v115
	v_cvt_pk_bf16_f32 v126, v118, v119
	v_cvt_pk_bf16_f32 v127, v120, v121
	v_cvt_pk_bf16_f32 v129, v116, v117
	global_store_dwordx4 v151, v[122:125], s[40:41]
	global_store_dwordx4 v151, v[126:129], s[40:41] offset:256
	s_nop 1
	v_or_b32_e32 v128, 0x80, v142
	v_cmp_lt_i32_e32 vcc, s33, v128
	s_and_saveexec_b64 s[26:27], vcc
	s_xor_b64 s[30:31], exec, s[26:27]
	s_movk_i32 s4, 0xac8
	v_cmp_eq_u32_e32 vcc, s4, v128
	s_and_b64 s[4:5], vcc, exec
	s_or_saveexec_b64 s[30:31], s[30:31]
	v_lshl_add_u64 v[122:123], s[38:39], 0, v[144:145]
	v_mov_b64_e32 v[124:125], 40
	v_mov_b64_e32 v[126:127], 44
	s_xor_b64 exec, exec, s[30:31]
	s_cbranch_execz .LBB0_466
	s_movk_i32 s26, 0xac0
	v_cmp_eq_u32_e32 vcc, s26, v128
	s_mov_b64 s[54:55], s[4:5]
	s_and_saveexec_b64 s[56:57], vcc
	s_cbranch_execz .LBB0_465
	global_store_dwordx4 v144, v[118:121], s[38:39]
	global_store_dwordx2 v144, v[114:115], s[38:39] offset:16
	s_or_b64 s[54:55], s[4:5], exec
	v_mov_b32_e32 v119, v117
	v_mov_b32_e32 v118, v116

.LBB0_466:
	s_or_b64 exec, exec, s[30:31]
	s_and_saveexec_b64 s[30:31], s[4:5]
	s_cbranch_execz .LBB0_468
	v_lshl_add_u64 v[114:115], v[122:123], 0, v[124:125]
	v_subrev_u32_e32 v115, s40, v114
	global_store_dword v115, v118, s[40:41]
	v_lshl_add_u64 v[114:115], v[122:123], 0, v[126:127]
	v_subrev_u32_e32 v115, s40, v114
	global_store_dword v115, v119, s[40:41]
.LBB0_468:
	s_or_b64 exec, exec, s[30:31]
	v_or_b32_e32 v144, 16, v140
	v_ashrrev_i32_e32 v145, 31, v144
	v_lshlrev_b64 v[114:115], 6, v[144:145]
	v_lshl_add_u64 v[150:151], s[42:43], 0, v[114:115]
	s_nop 0
	s_mov_b32 s4, 0xf800000
	s_waitcnt lgkmcnt(0)
	s_nop 0
	s_nop 0
	s_movk_i32 s4, 0x1600
	s_nop 0
	v_mov_b64_e32 v[116:117], s[36:37]
	v_mad_i64_i32 v[116:117], s[4:5], v144, s4, v[116:117]
	v_lshl_add_u64 v[116:117], v[142:143], 1, v[116:117]
	v_subrev_u32_e32 v117, s40, v116
	s_nop 0
	s_nop 1
	s_nop 1
	s_mov_b64 s[4:5], 0
	v_mov_b32_e32 v118, v245
	v_pk_mul_f32 v[112:113], v[112:113], v[118:119] op_sel_hi:[1,0]
	v_pk_mul_f32 v[110:111], v[110:111], v[118:119] op_sel_hi:[1,0]
	v_pk_mul_f32 v[120:121], v[108:109], v[118:119] op_sel_hi:[1,0]
	v_pk_mul_f32 v[108:109], v[106:107], v[118:119] op_sel_hi:[1,0]
	v_pk_mul_f32 v[104:105], v[104:105], v[118:119] op_sel_hi:[1,0]
	v_pk_mul_f32 v[102:103], v[102:103], v[118:119] op_sel_hi:[1,0]
	v_pk_mul_f32 v[100:101], v[100:101], v[118:119] op_sel_hi:[1,0]
	v_pk_mul_f32 v[98:99], v[98:99], v[118:119] op_sel_hi:[1,0]
	v_cvt_pk_bf16_f32 v106, v110, v111
	v_cvt_pk_bf16_f32 v107, v112, v113
	v_cvt_pk_bf16_f32 v108, v108, v109
	v_cvt_pk_bf16_f32 v109, v120, v121
	v_cmp_lt_i32_e32 vcc, s33, v128
	v_cvt_pk_bf16_f32 v110, v102, v103
	v_cvt_pk_bf16_f32 v111, v104, v105
	v_cvt_pk_bf16_f32 v112, v98, v99
	v_cvt_pk_bf16_f32 v113, v100, v101
	global_store_dwordx4 v117, v[106:109], s[40:41]
	global_store_dwordx4 v117, v[110:113], s[40:41] offset:256
	s_and_saveexec_b64 s[26:27], vcc
	s_xor_b64 s[30:31], exec, s[26:27]
	s_movk_i32 s4, 0xac8
	v_cmp_eq_u32_e32 vcc, s4, v128
	s_and_b64 s[4:5], vcc, exec
	s_or_saveexec_b64 s[30:31], s[30:31]
	v_lshl_add_u64 v[106:107], s[38:39], 0, v[114:115]
	v_mov_b64_e32 v[108:109], 40
	v_mov_b64_e32 v[110:111], 44
	s_xor_b64 exec, exec, s[30:31]
	s_cbranch_execz .LBB0_474
	s_movk_i32 s26, 0xac0
	v_cmp_eq_u32_e32 vcc, s26, v128
	s_mov_b64 s[54:55], s[4:5]
	s_and_saveexec_b64 s[56:57], vcc
	s_cbranch_execz .LBB0_473
	global_store_dwordx4 v114, v[102:105], s[38:39]
	global_store_dwordx2 v114, v[98:99], s[38:39] offset:16
	s_or_b64 s[54:55], s[4:5], exec
	v_mov_b32_e32 v103, v101
	v_mov_b32_e32 v102, v100

.LBB0_474:
	s_or_b64 exec, exec, s[30:31]
	s_and_saveexec_b64 s[30:31], s[4:5]
	s_cbranch_execz .LBB0_476
	v_lshl_add_u64 v[98:99], v[106:107], 0, v[108:109]
	v_subrev_u32_e32 v99, s40, v98
	global_store_dword v99, v102, s[40:41]
	v_lshl_add_u64 v[98:99], v[106:107], 0, v[110:111]
	v_subrev_u32_e32 v99, s40, v98
	global_store_dword v99, v103, s[40:41]
.LBB0_476:
	s_or_b64 exec, exec, s[30:31]
	v_or_b32_e32 v116, 32, v140
	v_ashrrev_i32_e32 v117, 31, v116
	v_lshlrev_b64 v[98:99], 6, v[116:117]
	v_lshl_add_u64 v[112:113], s[42:43], 0, v[98:99]
	s_nop 0
	s_mov_b32 s4, 0xf800000
	s_waitcnt lgkmcnt(0)
	s_nop 0
	s_nop 0
	s_movk_i32 s4, 0x1600
	s_nop 0
	v_mov_b64_e32 v[100:101], s[36:37]
	v_mad_i64_i32 v[100:101], s[4:5], v116, s4, v[100:101]
	v_lshl_add_u64 v[100:101], v[142:143], 1, v[100:101]
	v_subrev_u32_e32 v101, s40, v100
	s_nop 0
	s_nop 1
	s_nop 1
	s_mov_b64 s[4:5], 0
	v_mov_b32_e32 v102, v246
	v_pk_mul_f32 v[96:97], v[96:97], v[102:103] op_sel_hi:[1,0]
	v_pk_mul_f32 v[94:95], v[94:95], v[102:103] op_sel_hi:[1,0]
	v_pk_mul_f32 v[104:105], v[92:93], v[102:103] op_sel_hi:[1,0]
	v_pk_mul_f32 v[92:93], v[90:91], v[102:103] op_sel_hi:[1,0]
	v_pk_mul_f32 v[88:89], v[88:89], v[102:103] op_sel_hi:[1,0]
	v_pk_mul_f32 v[86:87], v[86:87], v[102:103] op_sel_hi:[1,0]
	v_pk_mul_f32 v[84:85], v[84:85], v[102:103] op_sel_hi:[1,0]
	v_pk_mul_f32 v[82:83], v[82:83], v[102:103] op_sel_hi:[1,0]
	v_cvt_pk_bf16_f32 v90, v94, v95
	v_cvt_pk_bf16_f32 v91, v96, v97
	v_cvt_pk_bf16_f32 v92, v92, v93
	v_cvt_pk_bf16_f32 v93, v104, v105
	v_cmp_lt_i32_e32 vcc, s33, v128
	v_cvt_pk_bf16_f32 v94, v86, v87
	v_cvt_pk_bf16_f32 v95, v88, v89
	v_cvt_pk_bf16_f32 v96, v82, v83
	v_cvt_pk_bf16_f32 v97, v84, v85
	global_store_dwordx4 v101, v[90:93], s[40:41]
	global_store_dwordx4 v101, v[94:97], s[40:41] offset:256
	s_and_saveexec_b64 s[26:27], vcc
	s_xor_b64 s[30:31], exec, s[26:27]
	s_movk_i32 s4, 0xac8
	v_cmp_eq_u32_e32 vcc, s4, v128
	s_and_b64 s[4:5], vcc, exec
	s_or_saveexec_b64 s[30:31], s[30:31]
	v_lshl_add_u64 v[90:91], s[38:39], 0, v[98:99]
	v_mov_b64_e32 v[92:93], 40
	v_mov_b64_e32 v[94:95], 44
	s_xor_b64 exec, exec, s[30:31]
	s_cbranch_execz .LBB0_482
	s_movk_i32 s26, 0xac0
	v_cmp_eq_u32_e32 vcc, s26, v128
	s_mov_b64 s[54:55], s[4:5]
	s_and_saveexec_b64 s[56:57], vcc
	s_cbranch_execz .LBB0_481
	global_store_dwordx4 v98, v[86:89], s[38:39]
	global_store_dwordx2 v98, v[82:83], s[38:39] offset:16
	s_or_b64 s[54:55], s[4:5], exec
	v_mov_b32_e32 v87, v85
	v_mov_b32_e32 v86, v84

.LBB0_482:
	s_or_b64 exec, exec, s[30:31]
	s_and_saveexec_b64 s[30:31], s[4:5]
	s_cbranch_execz .LBB0_484
	v_lshl_add_u64 v[82:83], v[90:91], 0, v[92:93]
	v_subrev_u32_e32 v83, s40, v82
	global_store_dword v83, v86, s[40:41]
	v_lshl_add_u64 v[82:83], v[90:91], 0, v[94:95]
	v_subrev_u32_e32 v83, s40, v82
	global_store_dword v83, v87, s[40:41]
.LBB0_484:
	s_or_b64 exec, exec, s[30:31]
	v_or_b32_e32 v100, 48, v140
	v_ashrrev_i32_e32 v101, 31, v100
	v_lshlrev_b64 v[82:83], 6, v[100:101]
	v_lshl_add_u64 v[96:97], s[42:43], 0, v[82:83]
	s_nop 0
	s_mov_b32 s4, 0xf800000
	s_waitcnt lgkmcnt(0)
	s_nop 0
	s_nop 0
	s_movk_i32 s4, 0x1600
	s_nop 0
	v_mov_b64_e32 v[84:85], s[36:37]
	v_mad_i64_i32 v[84:85], s[4:5], v100, s4, v[84:85]
	v_lshl_add_u64 v[84:85], v[142:143], 1, v[84:85]
	v_subrev_u32_e32 v85, s40, v84
	s_nop 0
	s_nop 1
	s_nop 1
	s_mov_b64 s[4:5], 0
	v_mov_b32_e32 v86, v247
	v_pk_mul_f32 v[80:81], v[80:81], v[86:87] op_sel_hi:[1,0]
	v_pk_mul_f32 v[78:79], v[78:79], v[86:87] op_sel_hi:[1,0]
	v_pk_mul_f32 v[88:89], v[76:77], v[86:87] op_sel_hi:[1,0]
	v_pk_mul_f32 v[76:77], v[74:75], v[86:87] op_sel_hi:[1,0]
	v_pk_mul_f32 v[72:73], v[72:73], v[86:87] op_sel_hi:[1,0]
	v_pk_mul_f32 v[70:71], v[70:71], v[86:87] op_sel_hi:[1,0]
	v_pk_mul_f32 v[68:69], v[68:69], v[86:87] op_sel_hi:[1,0]
	v_pk_mul_f32 v[66:67], v[66:67], v[86:87] op_sel_hi:[1,0]
	v_cvt_pk_bf16_f32 v74, v78, v79
	v_cvt_pk_bf16_f32 v75, v80, v81
	v_cvt_pk_bf16_f32 v76, v76, v77
	v_cvt_pk_bf16_f32 v77, v88, v89
	v_cmp_lt_i32_e32 vcc, s33, v128
	v_cvt_pk_bf16_f32 v78, v70, v71
	v_cvt_pk_bf16_f32 v79, v72, v73
	v_cvt_pk_bf16_f32 v80, v66, v67
	v_cvt_pk_bf16_f32 v81, v68, v69
	global_store_dwordx4 v85, v[74:77], s[40:41]
	global_store_dwordx4 v85, v[78:81], s[40:41] offset:256
	s_and_saveexec_b64 s[26:27], vcc
	s_xor_b64 s[30:31], exec, s[26:27]
	s_movk_i32 s4, 0xac8
	v_cmp_eq_u32_e32 vcc, s4, v128
	s_and_b64 s[4:5], vcc, exec
	s_or_saveexec_b64 s[30:31], s[30:31]
	v_lshl_add_u64 v[74:75], s[38:39], 0, v[82:83]
	v_mov_b64_e32 v[76:77], 40
	v_mov_b64_e32 v[78:79], 44
	s_xor_b64 exec, exec, s[30:31]
	s_cbranch_execz .LBB0_490
	s_movk_i32 s26, 0xac0
	v_cmp_eq_u32_e32 vcc, s26, v128
	s_mov_b64 s[54:55], s[4:5]
	s_and_saveexec_b64 s[56:57], vcc
	s_cbranch_execz .LBB0_489
	global_store_dwordx4 v82, v[70:73], s[38:39]
	global_store_dwordx2 v82, v[66:67], s[38:39] offset:16
	s_or_b64 s[54:55], s[4:5], exec
	v_mov_b32_e32 v71, v69
	v_mov_b32_e32 v70, v68

.LBB0_490:
	s_or_b64 exec, exec, s[30:31]
	s_and_saveexec_b64 s[30:31], s[4:5]
	s_cbranch_execz .LBB0_492
	v_lshl_add_u64 v[66:67], v[74:75], 0, v[76:77]
	v_subrev_u32_e32 v67, s40, v66
	global_store_dword v67, v70, s[40:41]
	v_lshl_add_u64 v[66:67], v[74:75], 0, v[78:79]
	v_subrev_u32_e32 v67, s40, v66
	global_store_dword v67, v71, s[40:41]
.LBB0_492:
	s_or_b64 exec, exec, s[30:31]
	v_add_u32_e32 v84, 0x80, v140
	v_ashrrev_i32_e32 v85, 31, v84
	v_lshlrev_b64 v[66:67], 6, v[84:85]
	v_lshl_add_u64 v[80:81], s[42:43], 0, v[66:67]
	s_nop 0
	s_mov_b32 s4, 0xf800000
	s_waitcnt lgkmcnt(0)
	s_nop 0
	s_nop 0
	s_movk_i32 s4, 0x1600
	s_nop 0
	v_mov_b64_e32 v[68:69], s[36:37]
	v_mad_i64_i32 v[68:69], s[4:5], v84, s4, v[68:69]
	v_lshl_add_u64 v[68:69], v[142:143], 1, v[68:69]
	v_subrev_u32_e32 v69, s40, v68
	s_nop 0
	s_nop 1
	s_nop 1
	s_mov_b64 s[4:5], 0
	v_mov_b32_e32 v70, v248
	v_pk_mul_f32 v[62:63], v[62:63], v[70:71] op_sel_hi:[1,0]
	v_pk_mul_f32 v[60:61], v[60:61], v[70:71] op_sel_hi:[1,0]
	v_pk_mul_f32 v[72:73], v[58:59], v[70:71] op_sel_hi:[1,0]
	v_pk_mul_f32 v[58:59], v[56:57], v[70:71] op_sel_hi:[1,0]
	v_pk_mul_f32 v[54:55], v[54:55], v[70:71] op_sel_hi:[1,0]
	v_pk_mul_f32 v[52:53], v[52:53], v[70:71] op_sel_hi:[1,0]
	v_pk_mul_f32 v[50:51], v[50:51], v[70:71] op_sel_hi:[1,0]
	v_pk_mul_f32 v[48:49], v[48:49], v[70:71] op_sel_hi:[1,0]
	v_cvt_pk_bf16_f32 v56, v60, v61
	v_cvt_pk_bf16_f32 v57, v62, v63
	v_cvt_pk_bf16_f32 v58, v58, v59
	v_cvt_pk_bf16_f32 v59, v72, v73
	v_cmp_lt_i32_e32 vcc, s33, v128
	v_cvt_pk_bf16_f32 v60, v52, v53
	v_cvt_pk_bf16_f32 v61, v54, v55
	v_cvt_pk_bf16_f32 v62, v48, v49
	v_cvt_pk_bf16_f32 v63, v50, v51
	global_store_dwordx4 v69, v[56:59], s[40:41]
	global_store_dwordx4 v69, v[60:63], s[40:41] offset:256
	s_and_saveexec_b64 s[26:27], vcc
	s_xor_b64 s[30:31], exec, s[26:27]
	s_movk_i32 s4, 0xac8
	v_cmp_eq_u32_e32 vcc, s4, v128
	s_and_b64 s[4:5], vcc, exec
	s_or_saveexec_b64 s[30:31], s[30:31]
	v_lshl_add_u64 v[56:57], s[38:39], 0, v[66:67]
	v_mov_b64_e32 v[58:59], 40
	v_mov_b64_e32 v[60:61], 44
	s_xor_b64 exec, exec, s[30:31]
	s_cbranch_execz .LBB0_498
	s_movk_i32 s26, 0xac0
	v_cmp_eq_u32_e32 vcc, s26, v128
	s_mov_b64 s[54:55], s[4:5]
	s_and_saveexec_b64 s[56:57], vcc
	s_cbranch_execz .LBB0_497
	global_store_dwordx4 v66, v[52:55], s[38:39]
	global_store_dwordx2 v66, v[48:49], s[38:39] offset:16
	s_or_b64 s[54:55], s[4:5], exec
	v_mov_b32_e32 v53, v51
	v_mov_b32_e32 v52, v50

.LBB0_498:
	s_or_b64 exec, exec, s[30:31]
	s_and_saveexec_b64 s[30:31], s[4:5]
	s_cbranch_execz .LBB0_500
	v_lshl_add_u64 v[48:49], v[56:57], 0, v[58:59]
	v_subrev_u32_e32 v49, s40, v48
	global_store_dword v49, v52, s[40:41]
	v_lshl_add_u64 v[48:49], v[56:57], 0, v[60:61]
	v_subrev_u32_e32 v49, s40, v48
	global_store_dword v49, v53, s[40:41]
.LBB0_500:
	s_or_b64 exec, exec, s[30:31]
	v_add_u32_e32 v62, 0x90, v140
	v_ashrrev_i32_e32 v63, 31, v62
	v_lshlrev_b64 v[48:49], 6, v[62:63]
	v_lshl_add_u64 v[66:67], s[42:43], 0, v[48:49]
	s_nop 0
	s_mov_b32 s4, 0xf800000
	s_waitcnt lgkmcnt(0)
	s_nop 0
	s_nop 0
	s_movk_i32 s4, 0x1600
	s_nop 0
	v_mov_b64_e32 v[50:51], s[36:37]
	v_mad_i64_i32 v[50:51], s[4:5], v62, s4, v[50:51]
	v_lshl_add_u64 v[50:51], v[142:143], 1, v[50:51]
	v_subrev_u32_e32 v51, s40, v50
	s_nop 0
	s_nop 1
	s_nop 1
	s_mov_b64 s[4:5], 0
	v_mov_b32_e32 v52, v249
	v_pk_mul_f32 v[46:47], v[46:47], v[52:53] op_sel_hi:[1,0]
	v_pk_mul_f32 v[44:45], v[44:45], v[52:53] op_sel_hi:[1,0]
	v_pk_mul_f32 v[54:55], v[42:43], v[52:53] op_sel_hi:[1,0]
	v_pk_mul_f32 v[42:43], v[40:41], v[52:53] op_sel_hi:[1,0]
	v_pk_mul_f32 v[38:39], v[38:39], v[52:53] op_sel_hi:[1,0]
	v_pk_mul_f32 v[36:37], v[36:37], v[52:53] op_sel_hi:[1,0]
	v_pk_mul_f32 v[34:35], v[34:35], v[52:53] op_sel_hi:[1,0]
	v_pk_mul_f32 v[32:33], v[32:33], v[52:53] op_sel_hi:[1,0]
	v_cvt_pk_bf16_f32 v40, v44, v45
	v_cvt_pk_bf16_f32 v41, v46, v47
	v_cvt_pk_bf16_f32 v42, v42, v43
	v_cvt_pk_bf16_f32 v43, v54, v55
	v_cmp_lt_i32_e32 vcc, s33, v128
	v_cvt_pk_bf16_f32 v44, v36, v37
	v_cvt_pk_bf16_f32 v45, v38, v39
	v_cvt_pk_bf16_f32 v46, v32, v33
	v_cvt_pk_bf16_f32 v47, v34, v35
	global_store_dwordx4 v51, v[40:43], s[40:41]
	global_store_dwordx4 v51, v[44:47], s[40:41] offset:256
	s_and_saveexec_b64 s[26:27], vcc
	s_xor_b64 s[30:31], exec, s[26:27]
	s_movk_i32 s4, 0xac8
	v_cmp_eq_u32_e32 vcc, s4, v128
	s_and_b64 s[4:5], vcc, exec
	s_or_saveexec_b64 s[30:31], s[30:31]
	v_lshl_add_u64 v[40:41], s[38:39], 0, v[48:49]
	v_mov_b64_e32 v[42:43], 40
	v_mov_b64_e32 v[44:45], 44
	s_xor_b64 exec, exec, s[30:31]
	s_cbranch_execz .LBB0_506
	s_movk_i32 s26, 0xac0
	v_cmp_eq_u32_e32 vcc, s26, v128
	s_mov_b64 s[54:55], s[4:5]
	s_and_saveexec_b64 s[56:57], vcc
	s_cbranch_execz .LBB0_505
	global_store_dwordx4 v48, v[36:39], s[38:39]
	global_store_dwordx2 v48, v[32:33], s[38:39] offset:16
	s_or_b64 s[54:55], s[4:5], exec
	v_mov_b32_e32 v37, v35
	v_mov_b32_e32 v36, v34

.LBB0_506:
	s_or_b64 exec, exec, s[30:31]
	s_and_saveexec_b64 s[30:31], s[4:5]
	s_cbranch_execz .LBB0_508
	v_lshl_add_u64 v[32:33], v[40:41], 0, v[42:43]
	v_subrev_u32_e32 v33, s40, v32
	global_store_dword v33, v36, s[40:41]
	v_lshl_add_u64 v[32:33], v[40:41], 0, v[44:45]
	v_subrev_u32_e32 v33, s40, v32
	global_store_dword v33, v37, s[40:41]
.LBB0_508:
	s_or_b64 exec, exec, s[30:31]
	v_add_u32_e32 v50, 0xa0, v140
	v_ashrrev_i32_e32 v51, 31, v50
	v_lshlrev_b64 v[32:33], 6, v[50:51]
	v_lshl_add_u64 v[46:47], s[42:43], 0, v[32:33]
	s_nop 0
	s_mov_b32 s4, 0xf800000
	s_waitcnt lgkmcnt(0)
	s_nop 0
	s_nop 0
	s_movk_i32 s4, 0x1600
	s_nop 0
	v_mov_b64_e32 v[34:35], s[36:37]
	v_mad_i64_i32 v[34:35], s[4:5], v50, s4, v[34:35]
	v_lshl_add_u64 v[34:35], v[142:143], 1, v[34:35]
	v_subrev_u32_e32 v35, s40, v34
	s_nop 0
	s_nop 1
	s_nop 1
	s_mov_b64 s[4:5], 0
	v_mov_b32_e32 v36, v250
	v_pk_mul_f32 v[30:31], v[30:31], v[36:37] op_sel_hi:[1,0]
	v_pk_mul_f32 v[28:29], v[28:29], v[36:37] op_sel_hi:[1,0]
	v_pk_mul_f32 v[38:39], v[26:27], v[36:37] op_sel_hi:[1,0]
	v_pk_mul_f32 v[26:27], v[24:25], v[36:37] op_sel_hi:[1,0]
	v_pk_mul_f32 v[22:23], v[22:23], v[36:37] op_sel_hi:[1,0]
	v_pk_mul_f32 v[20:21], v[20:21], v[36:37] op_sel_hi:[1,0]
	v_pk_mul_f32 v[18:19], v[18:19], v[36:37] op_sel_hi:[1,0]
	v_pk_mul_f32 v[16:17], v[16:17], v[36:37] op_sel_hi:[1,0]
	v_cvt_pk_bf16_f32 v24, v28, v29
	v_cvt_pk_bf16_f32 v25, v30, v31
	v_cvt_pk_bf16_f32 v26, v26, v27
	v_cvt_pk_bf16_f32 v27, v38, v39
	v_cmp_lt_i32_e32 vcc, s33, v128
	v_cvt_pk_bf16_f32 v28, v20, v21
	v_cvt_pk_bf16_f32 v29, v22, v23
	v_cvt_pk_bf16_f32 v30, v16, v17
	v_cvt_pk_bf16_f32 v31, v18, v19
	global_store_dwordx4 v35, v[24:27], s[40:41]
	global_store_dwordx4 v35, v[28:31], s[40:41] offset:256
	s_and_saveexec_b64 s[26:27], vcc
	s_xor_b64 s[30:31], exec, s[26:27]
	s_movk_i32 s4, 0xac8
	v_cmp_eq_u32_e32 vcc, s4, v128
	s_and_b64 s[4:5], vcc, exec
	s_or_saveexec_b64 s[30:31], s[30:31]
	v_lshl_add_u64 v[24:25], s[38:39], 0, v[32:33]
	v_mov_b64_e32 v[26:27], 40
	v_mov_b64_e32 v[28:29], 44
	s_xor_b64 exec, exec, s[30:31]
	s_cbranch_execz .LBB0_514
	s_movk_i32 s26, 0xac0
	v_cmp_eq_u32_e32 vcc, s26, v128
	s_mov_b64 s[54:55], s[4:5]
	s_and_saveexec_b64 s[56:57], vcc
	s_cbranch_execz .LBB0_513
	global_store_dwordx4 v32, v[20:23], s[38:39]
	global_store_dwordx2 v32, v[16:17], s[38:39] offset:16
	s_or_b64 s[54:55], s[4:5], exec
	v_mov_b32_e32 v21, v19
	v_mov_b32_e32 v20, v18

.LBB0_514:
	s_or_b64 exec, exec, s[30:31]
	s_and_saveexec_b64 s[30:31], s[4:5]
	s_cbranch_execz .LBB0_516
	v_lshl_add_u64 v[16:17], v[24:25], 0, v[26:27]
	v_subrev_u32_e32 v17, s40, v16
	global_store_dword v17, v20, s[40:41]
	v_lshl_add_u64 v[16:17], v[24:25], 0, v[28:29]
	v_subrev_u32_e32 v17, s40, v16
	global_store_dword v17, v21, s[40:41]
.LBB0_516:
	s_or_b64 exec, exec, s[30:31]
	v_add_u32_e32 v16, 0xb0, v140
	v_ashrrev_i32_e32 v17, 31, v16
	v_mov_b64_e32 v[18:19], s[36:37]
	s_movk_i32 s4, 0x1600
	v_mad_i64_i32 v[18:19], s[4:5], v16, s4, v[18:19]
	v_lshlrev_b64 v[16:17], 6, v[16:17]
	v_lshl_add_u64 v[32:33], s[42:43], 0, v[16:17]
	s_nop 0
	s_mov_b32 s4, 0xf800000
	v_lshl_add_u64 v[18:19], v[142:143], 1, v[18:19]
	v_subrev_u32_e32 v19, s40, v18
	s_waitcnt lgkmcnt(0)
	s_nop 0
	s_nop 0
	s_nop 0
	s_nop 0
	s_nop 0
	s_nop 0
	s_nop 0
	s_nop 1
	s_nop 1
	s_mov_b64 s[4:5], 0
	v_mov_b32_e32 v20, v251
	v_pk_mul_f32 v[14:15], v[14:15], v[20:21] op_sel_hi:[1,0]
	v_pk_mul_f32 v[12:13], v[12:13], v[20:21] op_sel_hi:[1,0]
	v_pk_mul_f32 v[22:23], v[10:11], v[20:21] op_sel_hi:[1,0]
	v_pk_mul_f32 v[10:11], v[8:9], v[20:21] op_sel_hi:[1,0]
	v_cvt_pk_bf16_f32 v8, v12, v13
	v_cvt_pk_bf16_f32 v9, v14, v15
	v_cvt_pk_bf16_f32 v10, v10, v11
	v_cvt_pk_bf16_f32 v11, v22, v23
	v_pk_mul_f32 v[6:7], v[6:7], v[20:21] op_sel_hi:[1,0]
	v_pk_mul_f32 v[4:5], v[4:5], v[20:21] op_sel_hi:[1,0]
	v_pk_mul_f32 v[2:3], v[2:3], v[20:21] op_sel_hi:[1,0]
	v_pk_mul_f32 v[0:1], v[0:1], v[20:21] op_sel_hi:[1,0]
	global_store_dwordx4 v19, v[8:11], s[40:41]
	v_cmp_lt_i32_e32 vcc, s33, v128
	s_nop 0
	v_cvt_pk_bf16_f32 v8, v4, v5
	v_cvt_pk_bf16_f32 v9, v6, v7
	v_cvt_pk_bf16_f32 v10, v0, v1
	v_cvt_pk_bf16_f32 v11, v2, v3
	global_store_dwordx4 v19, v[8:11], s[40:41] offset:256
	s_and_saveexec_b64 s[26:27], vcc
	s_xor_b64 s[30:31], exec, s[26:27]
	s_movk_i32 s4, 0xac8
	v_cmp_eq_u32_e32 vcc, s4, v128
	s_and_b64 s[4:5], vcc, exec
	s_or_saveexec_b64 s[30:31], s[30:31]
	v_lshl_add_u64 v[8:9], s[38:39], 0, v[16:17]
	v_mov_b64_e32 v[10:11], 40
	v_mov_b64_e32 v[12:13], 44
	s_xor_b64 exec, exec, s[30:31]
	s_cbranch_execz .LBB0_523
	s_movk_i32 s26, 0xac0
	v_cmp_eq_u32_e32 vcc, s26, v128
	s_mov_b64 s[54:55], s[4:5]
	s_and_saveexec_b64 s[56:57], vcc
	s_cbranch_execz .LBB0_521
	global_store_dwordx4 v16, v[4:7], s[38:39]
	global_store_dwordx2 v16, v[0:1], s[38:39] offset:16
	s_or_b64 s[54:55], s[4:5], exec
	v_mov_b32_e32 v5, v3
	v_mov_b32_e32 v4, v2

.LBB0_524:
	v_lshl_add_u64 v[0:1], v[8:9], 0, v[10:11]
	v_subrev_u32_e32 v1, s40, v0
	global_store_dword v1, v4, s[40:41]
	v_lshl_add_u64 v[0:1], v[8:9], 0, v[12:13]
	v_subrev_u32_e32 v1, s40, v0
	global_store_dword v1, v5, s[40:41]
	s_or_b64 exec, exec, s[30:31]
	s_andn2_b64 vcc, exec, s[0:1]
	s_mov_b64 s[0:1], -1
	s_cbranch_vccnz .LBB0_453

.LBB0_1164:
	v_readlane_b32 s76, v255, 6
	v_readlane_b32 s77, v255, 7
	v_readlane_b32 s78, v254, 51
	v_readlane_b32 s79, v254, 52
	v_lshl_add_u32 v138, s35, 8, v140
	v_lshl_or_b32 v136, s34, 8, v142
	v_ashrrev_i32_e32 v139, 31, v138
	v_ashrrev_i32_e32 v137, 31, v136
	v_lshlrev_b64 v[144:145], 10, v[138:139]
	v_lshl_add_u64 v[148:149], v[144:145], 0, v[136:137]
	v_readlane_b32 s52, v255, 6
	v_lshlrev_b64 v[150:151], 2, v[148:149]
	v_readlane_b32 s53, v255, 7
	v_lshlrev_b32_e32 v155, 1, v148
	s_nop 0
	v_mov_b32_e32 v153, v150
	global_load_dwordx4 v[144:147], v153, s[76:77]
	v_readlane_b32 s52, v254, 45
	v_readlane_b32 s58, v254, 51
	v_readlane_b32 s59, v254, 52
	v_readlane_b32 s53, v254, 46
	s_lshl_b32 s52, s34, 2
	v_mov_b32_e32 v157, v150
	v_readlane_b32 s54, v254, 47
	v_readlane_b32 s55, v254, 48
	s_ashr_i32 s53, s52, 31
	v_readlane_b32 s56, v254, 49
	v_readlane_b32 s57, v254, 50
	s_waitcnt vmcnt(0) lgkmcnt(0)
	v_pk_add_f32 v[128:129], v[128:129], v[146:147]
	v_pk_add_f32 v[126:127], v[126:127], v[144:145]
	v_cvt_pk_bf16_f32 v145, v128, v129
	v_cvt_pk_bf16_f32 v144, v126, v127
	global_store_dwordx4 v157, v[126:129], s[78:79]
	global_store_dwordx2 v155, v[144:145], s[6:7]
	global_load_dwordx4 v[144:147], v153, s[76:77] offset:64
	s_waitcnt vmcnt(0) lgkmcnt(0)
	v_pk_add_f32 v[124:125], v[124:125], v[146:147]
	v_pk_add_f32 v[122:123], v[122:123], v[144:145]
	v_cvt_pk_bf16_f32 v145, v124, v125
	v_cvt_pk_bf16_f32 v144, v122, v123
	global_store_dwordx4 v157, v[122:125], s[78:79] offset:64
	global_store_dwordx2 v155, v[144:145], s[6:7] offset:32
	global_load_dwordx4 v[144:147], v153, s[76:77] offset:512
	s_waitcnt vmcnt(0) lgkmcnt(0)
	v_pk_add_f32 v[146:147], v[120:121], v[146:147]
	v_pk_add_f32 v[144:145], v[118:119], v[144:145]
	v_cvt_pk_bf16_f32 v119, v146, v147
	v_cvt_pk_bf16_f32 v118, v144, v145
	global_store_dwordx4 v157, v[144:147], s[78:79] offset:512
	global_store_dwordx2 v155, v[118:119], s[6:7] offset:256
	global_load_dwordx4 v[148:151], v153, s[76:77] offset:576
	v_mul_f32_e32 v120, v127, v127
	v_mul_f32_e32 v121, v129, v129
	v_fmac_f32_e32 v120, v126, v126
	v_fmac_f32_e32 v121, v128, v128
	v_add_f32_e32 v120, v120, v121
	v_mul_f32_e32 v121, v123, v123
	v_mul_f32_e32 v123, v125, v125
	v_fmac_f32_e32 v121, v122, v122
	v_fmac_f32_e32 v123, v124, v124
	v_add_f32_e32 v121, v121, v123
	v_add_f32_e32 v120, v120, v121
	v_mul_f32_e32 v121, v145, v145
	v_mul_f32_e32 v122, v147, v147
	v_fmac_f32_e32 v121, v144, v144
	v_fmac_f32_e32 v122, v146, v146
	v_add_f32_e32 v121, v121, v122
	v_and_b32_e32 v119, 64, v197
	v_add_f32_e32 v124, v120, v121
	v_xor_b32_e32 v118, 16, v197
	v_add_u32_e32 v119, 64, v119
	v_cmp_lt_i32_e32 vcc, v118, v119
	s_waitcnt vmcnt(0) lgkmcnt(0)
	v_pk_add_f32 v[122:123], v[116:117], v[150:151]
	v_pk_add_f32 v[120:121], v[114:115], v[148:149]
	v_mul_f32_e32 v115, v123, v123
	v_mul_f32_e32 v114, v121, v121
	v_fmac_f32_e32 v114, v120, v120
	v_fmac_f32_e32 v115, v122, v122
	v_cndmask_b32_e32 v118, v197, v118, vcc
	v_add_f32_e32 v114, v114, v115
	v_lshlrev_b32_e32 v118, 2, v118
	v_add_f32_e32 v114, v124, v114
	ds_bpermute_b32 v115, v118, v114
	v_xor_b32_e32 v116, 32, v197
	v_cmp_lt_i32_e32 vcc, v116, v119
	global_store_dwordx4 v157, v[120:123], s[78:79] offset:576
	s_waitcnt lgkmcnt(0)
	v_add_f32_e32 v114, v114, v115
	v_cndmask_b32_e32 v116, v197, v116, vcc
	v_lshlrev_b32_e32 v116, 2, v116
	ds_bpermute_b32 v115, v116, v114
	v_cvt_pk_bf16_f32 v120, v120, v121
	v_cvt_pk_bf16_f32 v121, v122, v123
	global_store_dwordx2 v155, v[120:121], s[6:7] offset:288
	s_and_saveexec_b64 s[54:55], s[0:1]
	s_cbranch_execz .LBB0_1166
	v_readlane_b32 s34, v254, 43
	v_lshlrev_b64 v[120:121], 6, v[138:139]
	v_readlane_b32 s35, v254, 44
	v_lshl_add_u64 v[120:121], s[42:43], 0, v[120:121]
	s_mov_b32 s31, s35
	v_lshl_add_u64 v[120:121], s[52:53], 2, v[120:121]
	s_lshl_b32 s34, s64, 2
	v_writelane_b32 v254, s30, 43
	v_lshl_add_u64 v[120:121], v[120:121], 0, s[34:35]
	s_waitcnt lgkmcnt(0)
	v_add_f32_e32 v114, v114, v115
	v_writelane_b32 v254, s31, 44
	global_store_dword v[120:121], v114, off
.LBB0_1166:
	s_or_b64 exec, exec, s[54:55]
	v_or_b32_e32 v114, 16, v138
	s_waitcnt lgkmcnt(0)
	v_ashrrev_i32_e32 v115, 31, v114
	v_lshlrev_b64 v[120:121], 10, v[114:115]
	v_lshl_add_u64 v[124:125], v[120:121], 0, v[136:137]
	v_readlane_b32 s34, v255, 6
	v_lshlrev_b64 v[126:127], 2, v[124:125]
	v_readlane_b32 s35, v255, 7
	v_readlane_b32 s68, v254, 45
	v_readlane_b32 s74, v254, 51
	v_mov_b32_e32 v129, v126
	global_load_dwordx4 v[120:123], v129, s[76:77]
	v_readlane_b32 s75, v254, 52
	v_lshlrev_b32_e32 v125, 1, v124
	v_readlane_b32 s69, v254, 46
	v_mov_b32_e32 v127, v126
	v_readlane_b32 s70, v254, 47
	v_readlane_b32 s71, v254, 48
	v_readlane_b32 s72, v254, 49
	v_readlane_b32 s73, v254, 50
	s_waitcnt vmcnt(0) lgkmcnt(0)
	v_pk_add_f32 v[112:113], v[112:113], v[122:123]
	v_pk_add_f32 v[110:111], v[110:111], v[120:121]
	v_cvt_pk_bf16_f32 v121, v112, v113
	v_cvt_pk_bf16_f32 v120, v110, v111
	global_store_dwordx4 v127, v[110:113], s[78:79]
	global_store_dwordx2 v125, v[120:121], s[6:7]
	global_load_dwordx4 v[120:123], v129, s[76:77] offset:64
	v_mul_f32_e32 v111, v111, v111
	v_mul_f32_e32 v113, v113, v113
	v_fmac_f32_e32 v111, v110, v110
	v_fmac_f32_e32 v113, v112, v112
	v_add_f32_e32 v110, v111, v113
	s_waitcnt vmcnt(0) lgkmcnt(0)
	v_pk_add_f32 v[108:109], v[108:109], v[122:123]
	v_pk_add_f32 v[106:107], v[106:107], v[120:121]
	v_cvt_pk_bf16_f32 v121, v108, v109
	v_cvt_pk_bf16_f32 v120, v106, v107
	global_store_dwordx4 v127, v[106:109], s[78:79] offset:64
	global_store_dwordx2 v125, v[120:121], s[6:7] offset:32
	global_load_dwordx4 v[120:123], v129, s[76:77] offset:512
	v_mul_f32_e32 v107, v107, v107
	v_mul_f32_e32 v109, v109, v109
	v_fmac_f32_e32 v107, v106, v106
	v_fmac_f32_e32 v109, v108, v108
	v_add_f32_e32 v106, v107, v109
	v_add_f32_e32 v106, v110, v106
	s_waitcnt vmcnt(0) lgkmcnt(0)
	v_pk_add_f32 v[104:105], v[104:105], v[122:123]
	v_pk_add_f32 v[102:103], v[102:103], v[120:121]
	v_cvt_pk_bf16_f32 v121, v104, v105
	v_cvt_pk_bf16_f32 v120, v102, v103
	global_store_dwordx4 v127, v[102:105], s[78:79] offset:512
	global_store_dwordx2 v125, v[120:121], s[6:7] offset:256
	global_load_dwordx4 v[120:123], v129, s[76:77] offset:576
	v_mul_f32_e32 v103, v103, v103
	v_mul_f32_e32 v105, v105, v105
	v_fmac_f32_e32 v103, v102, v102
	v_fmac_f32_e32 v105, v104, v104
	v_add_f32_e32 v102, v103, v105
	v_add_f32_e32 v104, v106, v102
	s_waitcnt vmcnt(0) lgkmcnt(0)
	v_pk_add_f32 v[102:103], v[100:101], v[122:123]
	v_pk_add_f32 v[100:101], v[98:99], v[120:121]
	v_mul_f32_e32 v99, v103, v103
	v_mul_f32_e32 v98, v101, v101
	v_fmac_f32_e32 v98, v100, v100
	v_fmac_f32_e32 v99, v102, v102
	v_add_f32_e32 v98, v98, v99
	v_add_f32_e32 v98, v104, v98
	ds_bpermute_b32 v99, v118, v98
	global_store_dwordx4 v127, v[100:103], s[78:79] offset:576
	s_waitcnt lgkmcnt(0)
	v_add_f32_e32 v98, v98, v99
	ds_bpermute_b32 v99, v116, v98
	v_cvt_pk_bf16_f32 v100, v100, v101
	v_cvt_pk_bf16_f32 v101, v102, v103
	global_store_dwordx2 v125, v[100:101], s[6:7] offset:288
	s_and_saveexec_b64 s[54:55], s[0:1]
	s_cbranch_execz .LBB0_1168
	v_readlane_b32 s34, v254, 43
	v_lshlrev_b64 v[100:101], 6, v[114:115]
	v_readlane_b32 s35, v254, 44
	v_lshl_add_u64 v[100:101], s[42:43], 0, v[100:101]
	s_mov_b32 s31, s35
	v_lshl_add_u64 v[100:101], s[52:53], 2, v[100:101]
	s_lshl_b32 s34, s64, 2
	v_writelane_b32 v254, s30, 43
	v_lshl_add_u64 v[100:101], v[100:101], 0, s[34:35]
	s_waitcnt lgkmcnt(0)
	v_add_f32_e32 v98, v98, v99
	v_writelane_b32 v254, s31, 44
	global_store_dword v[100:101], v98, off
.LBB0_1168:
	s_or_b64 exec, exec, s[54:55]
	v_or_b32_e32 v98, 32, v138
	s_waitcnt lgkmcnt(0)
	v_ashrrev_i32_e32 v99, 31, v98
	v_lshlrev_b64 v[100:101], 10, v[98:99]
	v_lshl_add_u64 v[104:105], v[100:101], 0, v[136:137]
	v_readlane_b32 s34, v255, 6
	v_lshlrev_b64 v[106:107], 2, v[104:105]
	v_readlane_b32 s35, v255, 7
	v_readlane_b32 s68, v254, 45
	v_readlane_b32 s74, v254, 51
	v_mov_b32_e32 v109, v106
	global_load_dwordx4 v[100:103], v109, s[76:77]
	v_readlane_b32 s75, v254, 52
	v_lshlrev_b32_e32 v105, 1, v104
	v_readlane_b32 s69, v254, 46
	v_mov_b32_e32 v107, v106
	v_readlane_b32 s70, v254, 47
	v_readlane_b32 s71, v254, 48
	v_readlane_b32 s72, v254, 49
	v_readlane_b32 s73, v254, 50
	s_waitcnt vmcnt(0) lgkmcnt(0)
	v_pk_add_f32 v[96:97], v[96:97], v[102:103]
	v_pk_add_f32 v[94:95], v[94:95], v[100:101]
	v_cvt_pk_bf16_f32 v101, v96, v97
	v_cvt_pk_bf16_f32 v100, v94, v95
	global_store_dwordx4 v107, v[94:97], s[78:79]
	global_store_dwordx2 v105, v[100:101], s[6:7]
	global_load_dwordx4 v[100:103], v109, s[76:77] offset:64
	v_mul_f32_e32 v95, v95, v95
	v_mul_f32_e32 v97, v97, v97
	v_fmac_f32_e32 v95, v94, v94
	v_fmac_f32_e32 v97, v96, v96
	v_add_f32_e32 v94, v95, v97
	s_waitcnt vmcnt(0) lgkmcnt(0)
	v_pk_add_f32 v[92:93], v[92:93], v[102:103]
	v_pk_add_f32 v[90:91], v[90:91], v[100:101]
	v_cvt_pk_bf16_f32 v101, v92, v93
	v_cvt_pk_bf16_f32 v100, v90, v91
	global_store_dwordx4 v107, v[90:93], s[78:79] offset:64
	global_store_dwordx2 v105, v[100:101], s[6:7] offset:32
	global_load_dwordx4 v[100:103], v109, s[76:77] offset:512
	v_mul_f32_e32 v91, v91, v91
	v_mul_f32_e32 v93, v93, v93
	v_fmac_f32_e32 v91, v90, v90
	v_fmac_f32_e32 v93, v92, v92
	v_add_f32_e32 v90, v91, v93
	v_add_f32_e32 v90, v94, v90
	s_waitcnt vmcnt(0) lgkmcnt(0)
	v_pk_add_f32 v[88:89], v[88:89], v[102:103]
	v_pk_add_f32 v[86:87], v[86:87], v[100:101]
	v_cvt_pk_bf16_f32 v101, v88, v89
	v_cvt_pk_bf16_f32 v100, v86, v87
	global_store_dwordx4 v107, v[86:89], s[78:79] offset:512
	global_store_dwordx2 v105, v[100:101], s[6:7] offset:256
	global_load_dwordx4 v[100:103], v109, s[76:77] offset:576
	v_mul_f32_e32 v87, v87, v87
	v_mul_f32_e32 v89, v89, v89
	v_fmac_f32_e32 v87, v86, v86
	v_fmac_f32_e32 v89, v88, v88
	v_add_f32_e32 v86, v87, v89
	v_add_f32_e32 v88, v90, v86
	s_waitcnt vmcnt(0) lgkmcnt(0)
	v_pk_add_f32 v[86:87], v[84:85], v[102:103]
	v_pk_add_f32 v[84:85], v[82:83], v[100:101]
	v_mul_f32_e32 v83, v87, v87
	v_mul_f32_e32 v82, v85, v85
	v_fmac_f32_e32 v82, v84, v84
	v_fmac_f32_e32 v83, v86, v86
	v_add_f32_e32 v82, v82, v83
	v_add_f32_e32 v82, v88, v82
	ds_bpermute_b32 v83, v118, v82
	global_store_dwordx4 v107, v[84:87], s[78:79] offset:576
	s_waitcnt lgkmcnt(0)
	v_add_f32_e32 v82, v82, v83
	ds_bpermute_b32 v83, v116, v82
	v_cvt_pk_bf16_f32 v84, v84, v85
	v_cvt_pk_bf16_f32 v85, v86, v87
	global_store_dwordx2 v105, v[84:85], s[6:7] offset:288
	s_mov_b64 s[54:55], exec
	v_readlane_b32 s92, v252, 6
	s_and_b64 s[34:35], s[54:55], s[0:1]
	v_readlane_b32 s93, v252, 7
	v_mov_b32_e32 v200, v202
	s_mov_b64 exec, s[34:35]
	s_cbranch_execz .LBB0_1170
	v_readlane_b32 s34, v254, 43
	v_lshlrev_b64 v[84:85], 6, v[98:99]
	v_readlane_b32 s35, v254, 44
	v_lshl_add_u64 v[84:85], s[42:43], 0, v[84:85]
	s_mov_b32 s31, s35
	v_lshl_add_u64 v[84:85], s[52:53], 2, v[84:85]
	s_lshl_b32 s34, s64, 2
	v_writelane_b32 v254, s30, 43
	v_lshl_add_u64 v[84:85], v[84:85], 0, s[34:35]
	s_waitcnt lgkmcnt(0)
	v_add_f32_e32 v82, v82, v83
	v_writelane_b32 v254, s31, 44
	global_store_dword v[84:85], v82, off
.LBB0_1170:
	s_or_b64 exec, exec, s[54:55]
	v_or_b32_e32 v82, 48, v138
	s_waitcnt lgkmcnt(0)
	v_ashrrev_i32_e32 v83, 31, v82
	v_lshlrev_b64 v[84:85], 10, v[82:83]
	v_lshl_add_u64 v[88:89], v[84:85], 0, v[136:137]
	v_readlane_b32 s34, v255, 6
	v_lshlrev_b64 v[90:91], 2, v[88:89]
	v_readlane_b32 s35, v255, 7
	v_readlane_b32 s84, v254, 45
	v_readlane_b32 s90, v254, 51
	v_mov_b32_e32 v93, v90
	global_load_dwordx4 v[84:87], v93, s[76:77]
	v_readlane_b32 s91, v254, 52
	v_lshlrev_b32_e32 v89, 1, v88
	v_readlane_b32 s85, v254, 46
	v_mov_b32_e32 v91, v90
	v_readlane_b32 s86, v254, 47
	v_readlane_b32 s87, v254, 48
	v_readlane_b32 s88, v254, 49
	v_readlane_b32 s89, v254, 50
	s_waitcnt vmcnt(0) lgkmcnt(0)
	v_pk_add_f32 v[80:81], v[80:81], v[86:87]
	v_pk_add_f32 v[78:79], v[78:79], v[84:85]
	v_cvt_pk_bf16_f32 v85, v80, v81
	v_cvt_pk_bf16_f32 v84, v78, v79
	global_store_dwordx4 v91, v[78:81], s[78:79]
	global_store_dwordx2 v89, v[84:85], s[6:7]
	global_load_dwordx4 v[84:87], v93, s[76:77] offset:64
	v_mul_f32_e32 v79, v79, v79
	v_mul_f32_e32 v81, v81, v81
	v_fmac_f32_e32 v79, v78, v78
	v_fmac_f32_e32 v81, v80, v80
	v_add_f32_e32 v78, v79, v81
	s_waitcnt vmcnt(0) lgkmcnt(0)
	v_pk_add_f32 v[76:77], v[76:77], v[86:87]
	v_pk_add_f32 v[74:75], v[74:75], v[84:85]
	v_cvt_pk_bf16_f32 v85, v76, v77
	v_cvt_pk_bf16_f32 v84, v74, v75
	global_store_dwordx4 v91, v[74:77], s[78:79] offset:64
	global_store_dwordx2 v89, v[84:85], s[6:7] offset:32
	global_load_dwordx4 v[84:87], v93, s[76:77] offset:512
	v_mul_f32_e32 v75, v75, v75
	v_mul_f32_e32 v77, v77, v77
	v_fmac_f32_e32 v75, v74, v74
	v_fmac_f32_e32 v77, v76, v76
	v_add_f32_e32 v74, v75, v77
	v_add_f32_e32 v74, v78, v74
	s_waitcnt vmcnt(0) lgkmcnt(0)
	v_pk_add_f32 v[72:73], v[72:73], v[86:87]
	v_pk_add_f32 v[70:71], v[70:71], v[84:85]
	v_cvt_pk_bf16_f32 v85, v72, v73
	v_cvt_pk_bf16_f32 v84, v70, v71
	global_store_dwordx4 v91, v[70:73], s[78:79] offset:512
	global_store_dwordx2 v89, v[84:85], s[6:7] offset:256
	global_load_dwordx4 v[84:87], v93, s[76:77] offset:576
	v_mul_f32_e32 v71, v71, v71
	v_mul_f32_e32 v73, v73, v73
	v_fmac_f32_e32 v71, v70, v70
	v_fmac_f32_e32 v73, v72, v72
	v_add_f32_e32 v70, v71, v73
	v_add_f32_e32 v72, v74, v70
	s_waitcnt vmcnt(0) lgkmcnt(0)
	v_pk_add_f32 v[70:71], v[68:69], v[86:87]
	v_pk_add_f32 v[68:69], v[66:67], v[84:85]
	v_mul_f32_e32 v67, v71, v71
	v_mul_f32_e32 v66, v69, v69
	v_fmac_f32_e32 v66, v68, v68
	v_fmac_f32_e32 v67, v70, v70
	v_add_f32_e32 v66, v66, v67
	v_add_f32_e32 v66, v72, v66
	ds_bpermute_b32 v67, v118, v66
	global_store_dwordx4 v91, v[68:71], s[78:79] offset:576
	s_waitcnt lgkmcnt(0)
	v_add_f32_e32 v66, v66, v67
	ds_bpermute_b32 v67, v116, v66
	v_cvt_pk_bf16_f32 v68, v68, v69
	v_cvt_pk_bf16_f32 v69, v70, v71
	global_store_dwordx2 v89, v[68:69], s[6:7] offset:288
	s_and_saveexec_b64 s[54:55], s[0:1]
	s_cbranch_execz .LBB0_1172
	v_readlane_b32 s34, v254, 43
	v_lshlrev_b64 v[68:69], 6, v[82:83]
	v_readlane_b32 s35, v254, 44
	v_lshl_add_u64 v[68:69], s[42:43], 0, v[68:69]
	s_mov_b32 s31, s35
	v_lshl_add_u64 v[68:69], s[52:53], 2, v[68:69]
	s_lshl_b32 s34, s64, 2
	v_writelane_b32 v254, s30, 43
	v_lshl_add_u64 v[68:69], v[68:69], 0, s[34:35]
	s_waitcnt lgkmcnt(0)
	v_add_f32_e32 v66, v66, v67
	v_writelane_b32 v254, s31, 44
	global_store_dword v[68:69], v66, off
.LBB0_1172:
	s_or_b64 exec, exec, s[54:55]
	v_add_u32_e32 v66, 0x80, v138
	s_waitcnt lgkmcnt(0)
	v_ashrrev_i32_e32 v67, 31, v66
	v_lshlrev_b64 v[68:69], 10, v[66:67]
	v_lshl_add_u64 v[72:73], v[68:69], 0, v[136:137]
	v_readlane_b32 s34, v255, 6
	v_lshlrev_b64 v[74:75], 2, v[72:73]
	v_readlane_b32 s35, v255, 7
	v_readlane_b32 s84, v254, 45
	v_readlane_b32 s90, v254, 51
	v_mov_b32_e32 v77, v74
	global_load_dwordx4 v[68:71], v77, s[76:77]
	v_readlane_b32 s91, v254, 52
	v_lshlrev_b32_e32 v73, 1, v72
	v_readlane_b32 s85, v254, 46
	v_mov_b32_e32 v75, v74
	v_readlane_b32 s86, v254, 47
	v_readlane_b32 s87, v254, 48
	v_readlane_b32 s88, v254, 49
	v_readlane_b32 s89, v254, 50
	s_waitcnt vmcnt(0) lgkmcnt(0)
	v_pk_add_f32 v[62:63], v[62:63], v[70:71]
	v_pk_add_f32 v[60:61], v[60:61], v[68:69]
	v_cvt_pk_bf16_f32 v69, v62, v63
	v_cvt_pk_bf16_f32 v68, v60, v61
	global_store_dwordx4 v75, v[60:63], s[78:79]
	global_store_dwordx2 v73, v[68:69], s[6:7]
	global_load_dwordx4 v[68:71], v77, s[76:77] offset:64
	v_mul_f32_e32 v61, v61, v61
	v_mul_f32_e32 v63, v63, v63
	v_fmac_f32_e32 v61, v60, v60
	v_fmac_f32_e32 v63, v62, v62
	v_add_f32_e32 v60, v61, v63
	s_waitcnt vmcnt(0) lgkmcnt(0)
	v_pk_add_f32 v[58:59], v[58:59], v[70:71]
	v_pk_add_f32 v[56:57], v[56:57], v[68:69]
	v_cvt_pk_bf16_f32 v69, v58, v59
	v_cvt_pk_bf16_f32 v68, v56, v57
	global_store_dwordx4 v75, v[56:59], s[78:79] offset:64
	global_store_dwordx2 v73, v[68:69], s[6:7] offset:32
	global_load_dwordx4 v[68:71], v77, s[76:77] offset:512
	v_mul_f32_e32 v57, v57, v57
	v_mul_f32_e32 v59, v59, v59
	v_fmac_f32_e32 v57, v56, v56
	v_fmac_f32_e32 v59, v58, v58
	v_add_f32_e32 v56, v57, v59
	v_add_f32_e32 v56, v60, v56
	s_waitcnt vmcnt(0) lgkmcnt(0)
	v_pk_add_f32 v[54:55], v[54:55], v[70:71]
	v_pk_add_f32 v[52:53], v[52:53], v[68:69]
	v_cvt_pk_bf16_f32 v69, v54, v55
	v_cvt_pk_bf16_f32 v68, v52, v53
	global_store_dwordx4 v75, v[52:55], s[78:79] offset:512
	global_store_dwordx2 v73, v[68:69], s[6:7] offset:256
	global_load_dwordx4 v[68:71], v77, s[76:77] offset:576
	v_mul_f32_e32 v53, v53, v53
	v_mul_f32_e32 v55, v55, v55
	v_fmac_f32_e32 v53, v52, v52
	v_fmac_f32_e32 v55, v54, v54
	v_add_f32_e32 v52, v53, v55
	v_add_f32_e32 v54, v56, v52
	s_waitcnt vmcnt(0) lgkmcnt(0)
	v_pk_add_f32 v[52:53], v[50:51], v[70:71]
	v_pk_add_f32 v[50:51], v[48:49], v[68:69]
	v_mul_f32_e32 v49, v53, v53
	v_mul_f32_e32 v48, v51, v51
	v_fmac_f32_e32 v48, v50, v50
	v_fmac_f32_e32 v49, v52, v52
	v_add_f32_e32 v48, v48, v49
	v_add_f32_e32 v48, v54, v48
	ds_bpermute_b32 v49, v118, v48
	global_store_dwordx4 v75, v[50:53], s[78:79] offset:576
	s_waitcnt lgkmcnt(0)
	v_add_f32_e32 v48, v48, v49
	ds_bpermute_b32 v49, v116, v48
	v_cvt_pk_bf16_f32 v50, v50, v51
	v_cvt_pk_bf16_f32 v51, v52, v53
	global_store_dwordx2 v73, v[50:51], s[6:7] offset:288
	s_and_saveexec_b64 s[54:55], s[0:1]
	s_cbranch_execz .LBB0_1174
	v_readlane_b32 s34, v254, 43
	v_lshlrev_b64 v[50:51], 6, v[66:67]
	v_readlane_b32 s35, v254, 44
	v_lshl_add_u64 v[50:51], s[42:43], 0, v[50:51]
	s_mov_b32 s31, s35
	v_lshl_add_u64 v[50:51], s[52:53], 2, v[50:51]
	s_lshl_b32 s34, s64, 2
	v_writelane_b32 v254, s30, 43
	v_lshl_add_u64 v[50:51], v[50:51], 0, s[34:35]
	s_waitcnt lgkmcnt(0)
	v_add_f32_e32 v48, v48, v49
	v_writelane_b32 v254, s31, 44
	global_store_dword v[50:51], v48, off
.LBB0_1174:
	s_or_b64 exec, exec, s[54:55]
	v_add_u32_e32 v48, 0x90, v138
	s_waitcnt lgkmcnt(0)
	v_ashrrev_i32_e32 v49, 31, v48
	v_lshlrev_b64 v[50:51], 10, v[48:49]
	v_lshl_add_u64 v[54:55], v[50:51], 0, v[136:137]
	v_readlane_b32 s34, v255, 6
	v_lshlrev_b64 v[56:57], 2, v[54:55]
	v_readlane_b32 s35, v255, 7
	v_readlane_b32 s84, v254, 45
	v_readlane_b32 s90, v254, 51
	v_mov_b32_e32 v59, v56
	global_load_dwordx4 v[50:53], v59, s[76:77]
	v_readlane_b32 s91, v254, 52
	v_lshlrev_b32_e32 v55, 1, v54
	v_readlane_b32 s85, v254, 46
	v_mov_b32_e32 v57, v56
	v_readlane_b32 s86, v254, 47
	v_readlane_b32 s87, v254, 48
	v_readlane_b32 s88, v254, 49
	v_readlane_b32 s89, v254, 50
	s_waitcnt vmcnt(0) lgkmcnt(0)
	v_pk_add_f32 v[46:47], v[46:47], v[52:53]
	v_pk_add_f32 v[44:45], v[44:45], v[50:51]
	v_cvt_pk_bf16_f32 v51, v46, v47
	v_cvt_pk_bf16_f32 v50, v44, v45
	global_store_dwordx4 v57, v[44:47], s[78:79]
	global_store_dwordx2 v55, v[50:51], s[6:7]
	global_load_dwordx4 v[50:53], v59, s[76:77] offset:64
	v_mul_f32_e32 v45, v45, v45
	v_mul_f32_e32 v47, v47, v47
	v_fmac_f32_e32 v45, v44, v44
	v_fmac_f32_e32 v47, v46, v46
	v_add_f32_e32 v44, v45, v47
	s_waitcnt vmcnt(0) lgkmcnt(0)
	v_pk_add_f32 v[42:43], v[42:43], v[52:53]
	v_pk_add_f32 v[40:41], v[40:41], v[50:51]
	v_cvt_pk_bf16_f32 v51, v42, v43
	v_cvt_pk_bf16_f32 v50, v40, v41
	global_store_dwordx4 v57, v[40:43], s[78:79] offset:64
	global_store_dwordx2 v55, v[50:51], s[6:7] offset:32
	global_load_dwordx4 v[50:53], v59, s[76:77] offset:512
	v_mul_f32_e32 v41, v41, v41
	v_mul_f32_e32 v43, v43, v43
	v_fmac_f32_e32 v41, v40, v40
	v_fmac_f32_e32 v43, v42, v42
	v_add_f32_e32 v40, v41, v43
	v_add_f32_e32 v40, v44, v40
	s_waitcnt vmcnt(0) lgkmcnt(0)
	v_pk_add_f32 v[38:39], v[38:39], v[52:53]
	v_pk_add_f32 v[36:37], v[36:37], v[50:51]
	v_cvt_pk_bf16_f32 v51, v38, v39
	v_cvt_pk_bf16_f32 v50, v36, v37
	global_store_dwordx4 v57, v[36:39], s[78:79] offset:512
	global_store_dwordx2 v55, v[50:51], s[6:7] offset:256
	global_load_dwordx4 v[50:53], v59, s[76:77] offset:576
	v_mul_f32_e32 v37, v37, v37
	v_mul_f32_e32 v39, v39, v39
	v_fmac_f32_e32 v37, v36, v36
	v_fmac_f32_e32 v39, v38, v38
	v_add_f32_e32 v36, v37, v39
	v_add_f32_e32 v38, v40, v36
	s_waitcnt vmcnt(0) lgkmcnt(0)
	v_pk_add_f32 v[36:37], v[34:35], v[52:53]
	v_pk_add_f32 v[34:35], v[32:33], v[50:51]
	v_mul_f32_e32 v33, v37, v37
	v_mul_f32_e32 v32, v35, v35
	v_fmac_f32_e32 v32, v34, v34
	v_fmac_f32_e32 v33, v36, v36
	v_add_f32_e32 v32, v32, v33
	v_add_f32_e32 v32, v38, v32
	ds_bpermute_b32 v33, v118, v32
	global_store_dwordx4 v57, v[34:37], s[78:79] offset:576
	s_waitcnt lgkmcnt(0)
	v_add_f32_e32 v32, v32, v33
	ds_bpermute_b32 v33, v116, v32
	v_cvt_pk_bf16_f32 v34, v34, v35
	v_cvt_pk_bf16_f32 v35, v36, v37
	global_store_dwordx2 v55, v[34:35], s[6:7] offset:288
	s_and_saveexec_b64 s[54:55], s[0:1]
	s_cbranch_execz .LBB0_1176
	v_readlane_b32 s34, v254, 43
	v_lshlrev_b64 v[34:35], 6, v[48:49]
	v_readlane_b32 s35, v254, 44
	v_lshl_add_u64 v[34:35], s[42:43], 0, v[34:35]
	s_mov_b32 s31, s35
	v_lshl_add_u64 v[34:35], s[52:53], 2, v[34:35]
	s_lshl_b32 s34, s64, 2
	v_writelane_b32 v254, s30, 43
	v_lshl_add_u64 v[34:35], v[34:35], 0, s[34:35]
	s_waitcnt lgkmcnt(0)
	v_add_f32_e32 v32, v32, v33
	v_writelane_b32 v254, s31, 44
	global_store_dword v[34:35], v32, off
.LBB0_1176:
	s_or_b64 exec, exec, s[54:55]
	v_add_u32_e32 v32, 0xa0, v138
	s_waitcnt lgkmcnt(0)
	v_ashrrev_i32_e32 v33, 31, v32
	v_lshlrev_b64 v[34:35], 10, v[32:33]
	v_lshl_add_u64 v[38:39], v[34:35], 0, v[136:137]
	v_readlane_b32 s34, v255, 6
	v_lshlrev_b64 v[40:41], 2, v[38:39]
	v_readlane_b32 s35, v255, 7
	v_readlane_b32 s84, v254, 45
	v_readlane_b32 s90, v254, 51
	v_mov_b32_e32 v43, v40
	global_load_dwordx4 v[34:37], v43, s[76:77]
	v_readlane_b32 s91, v254, 52
	v_lshlrev_b32_e32 v39, 1, v38
	v_readlane_b32 s85, v254, 46
	v_mov_b32_e32 v41, v40
	v_readlane_b32 s86, v254, 47
	v_readlane_b32 s87, v254, 48
	v_readlane_b32 s88, v254, 49
	v_readlane_b32 s89, v254, 50
	s_waitcnt vmcnt(0) lgkmcnt(0)
	v_pk_add_f32 v[30:31], v[30:31], v[36:37]
	v_pk_add_f32 v[28:29], v[28:29], v[34:35]
	v_cvt_pk_bf16_f32 v35, v30, v31
	v_cvt_pk_bf16_f32 v34, v28, v29
	global_store_dwordx4 v41, v[28:31], s[78:79]
	global_store_dwordx2 v39, v[34:35], s[6:7]
	global_load_dwordx4 v[34:37], v43, s[76:77] offset:64
	v_mul_f32_e32 v29, v29, v29
	v_mul_f32_e32 v31, v31, v31
	v_fmac_f32_e32 v29, v28, v28
	v_fmac_f32_e32 v31, v30, v30
	v_add_f32_e32 v28, v29, v31
	s_waitcnt vmcnt(0) lgkmcnt(0)
	v_pk_add_f32 v[26:27], v[26:27], v[36:37]
	v_pk_add_f32 v[24:25], v[24:25], v[34:35]
	v_cvt_pk_bf16_f32 v35, v26, v27
	v_cvt_pk_bf16_f32 v34, v24, v25
	global_store_dwordx4 v41, v[24:27], s[78:79] offset:64
	global_store_dwordx2 v39, v[34:35], s[6:7] offset:32
	global_load_dwordx4 v[34:37], v43, s[76:77] offset:512
	v_mul_f32_e32 v25, v25, v25
	v_mul_f32_e32 v27, v27, v27
	v_fmac_f32_e32 v25, v24, v24
	v_fmac_f32_e32 v27, v26, v26
	v_add_f32_e32 v24, v25, v27
	v_add_f32_e32 v24, v28, v24
	s_waitcnt vmcnt(0) lgkmcnt(0)
	v_pk_add_f32 v[22:23], v[22:23], v[36:37]
	v_pk_add_f32 v[20:21], v[20:21], v[34:35]
	v_cvt_pk_bf16_f32 v35, v22, v23
	v_cvt_pk_bf16_f32 v34, v20, v21
	global_store_dwordx4 v41, v[20:23], s[78:79] offset:512
	global_store_dwordx2 v39, v[34:35], s[6:7] offset:256
	global_load_dwordx4 v[34:37], v43, s[76:77] offset:576
	v_mul_f32_e32 v21, v21, v21
	v_mul_f32_e32 v23, v23, v23
	v_fmac_f32_e32 v21, v20, v20
	v_fmac_f32_e32 v23, v22, v22
	v_add_f32_e32 v20, v21, v23
	v_add_f32_e32 v22, v24, v20
	s_waitcnt vmcnt(0) lgkmcnt(0)
	v_pk_add_f32 v[20:21], v[18:19], v[36:37]
	v_pk_add_f32 v[18:19], v[16:17], v[34:35]
	v_mul_f32_e32 v17, v21, v21
	v_mul_f32_e32 v16, v19, v19
	v_fmac_f32_e32 v16, v18, v18
	v_fmac_f32_e32 v17, v20, v20
	v_add_f32_e32 v16, v16, v17
	v_add_f32_e32 v16, v22, v16
	ds_bpermute_b32 v17, v118, v16
	global_store_dwordx4 v41, v[18:21], s[78:79] offset:576
	s_waitcnt lgkmcnt(0)
	v_add_f32_e32 v16, v16, v17
	ds_bpermute_b32 v17, v116, v16
	v_cvt_pk_bf16_f32 v18, v18, v19
	v_cvt_pk_bf16_f32 v19, v20, v21
	global_store_dwordx2 v39, v[18:19], s[6:7] offset:288
	s_and_saveexec_b64 s[54:55], s[0:1]
	s_cbranch_execz .LBB0_1178
	v_readlane_b32 s34, v254, 43
	v_lshlrev_b64 v[18:19], 6, v[32:33]
	v_readlane_b32 s35, v254, 44
	v_lshl_add_u64 v[18:19], s[42:43], 0, v[18:19]
	s_mov_b32 s31, s35
	v_lshl_add_u64 v[18:19], s[52:53], 2, v[18:19]
	s_lshl_b32 s34, s64, 2
	v_writelane_b32 v254, s30, 43
	v_lshl_add_u64 v[18:19], v[18:19], 0, s[34:35]
	s_waitcnt lgkmcnt(0)
	v_add_f32_e32 v16, v16, v17
	v_writelane_b32 v254, s31, 44
	global_store_dword v[18:19], v16, off
.LBB0_1178:
	s_or_b64 exec, exec, s[54:55]
	v_add_u32_e32 v16, 0xb0, v138
	s_waitcnt lgkmcnt(0)
	v_ashrrev_i32_e32 v17, 31, v16
	v_lshlrev_b64 v[18:19], 10, v[16:17]
	v_lshl_add_u64 v[22:23], v[18:19], 0, v[136:137]
	v_readlane_b32 s34, v255, 6
	v_lshlrev_b64 v[24:25], 2, v[22:23]
	v_readlane_b32 s35, v255, 7
	v_readlane_b32 s84, v254, 45
	v_readlane_b32 s90, v254, 51
	v_mov_b32_e32 v27, v24
	global_load_dwordx4 v[18:21], v27, s[76:77]
	v_readlane_b32 s91, v254, 52
	v_lshlrev_b32_e32 v23, 1, v22
	v_readlane_b32 s85, v254, 46
	v_mov_b32_e32 v25, v24
	v_readlane_b32 s86, v254, 47
	v_readlane_b32 s87, v254, 48
	v_readlane_b32 s88, v254, 49
	v_readlane_b32 s89, v254, 50
	s_waitcnt vmcnt(0) lgkmcnt(0)
	v_pk_add_f32 v[14:15], v[14:15], v[20:21]
	v_pk_add_f32 v[12:13], v[12:13], v[18:19]
	v_cvt_pk_bf16_f32 v19, v14, v15
	v_cvt_pk_bf16_f32 v18, v12, v13
	global_store_dwordx4 v25, v[12:15], s[78:79]
	global_store_dwordx2 v23, v[18:19], s[6:7]
	global_load_dwordx4 v[18:21], v27, s[76:77] offset:64
	v_mul_f32_e32 v13, v13, v13
	v_mul_f32_e32 v15, v15, v15
	v_fmac_f32_e32 v13, v12, v12
	v_fmac_f32_e32 v15, v14, v14
	v_add_f32_e32 v12, v13, v15
	s_waitcnt vmcnt(0) lgkmcnt(0)
	v_pk_add_f32 v[10:11], v[10:11], v[20:21]
	v_pk_add_f32 v[8:9], v[8:9], v[18:19]
	v_cvt_pk_bf16_f32 v19, v10, v11
	v_cvt_pk_bf16_f32 v18, v8, v9
	global_store_dwordx4 v25, v[8:11], s[78:79] offset:64
	global_store_dwordx2 v23, v[18:19], s[6:7] offset:32
	global_load_dwordx4 v[18:21], v27, s[76:77] offset:512
	v_mul_f32_e32 v9, v9, v9
	v_mul_f32_e32 v11, v11, v11
	v_fmac_f32_e32 v9, v8, v8
	v_fmac_f32_e32 v11, v10, v10
	v_add_f32_e32 v8, v9, v11
	v_add_f32_e32 v8, v12, v8
	s_waitcnt vmcnt(0) lgkmcnt(0)
	v_pk_add_f32 v[6:7], v[6:7], v[20:21]
	v_pk_add_f32 v[4:5], v[4:5], v[18:19]
	v_cvt_pk_bf16_f32 v19, v6, v7
	v_cvt_pk_bf16_f32 v18, v4, v5
	global_store_dwordx4 v25, v[4:7], s[78:79] offset:512
	global_store_dwordx2 v23, v[18:19], s[6:7] offset:256
	global_load_dwordx4 v[18:21], v27, s[76:77] offset:576
	v_mul_f32_e32 v5, v5, v5
	v_mul_f32_e32 v7, v7, v7
	v_fmac_f32_e32 v5, v4, v4
	v_fmac_f32_e32 v7, v6, v6
	v_add_f32_e32 v4, v5, v7
	v_add_f32_e32 v6, v8, v4
	s_waitcnt vmcnt(0) lgkmcnt(0)
	v_pk_add_f32 v[4:5], v[2:3], v[20:21]
	v_pk_add_f32 v[2:3], v[0:1], v[18:19]
	v_mul_f32_e32 v1, v5, v5
	v_mul_f32_e32 v0, v3, v3
	v_fmac_f32_e32 v0, v2, v2
	v_fmac_f32_e32 v1, v4, v4
	v_add_f32_e32 v0, v0, v1
	v_add_f32_e32 v0, v6, v0
	ds_bpermute_b32 v1, v118, v0
	global_store_dwordx4 v25, v[2:5], s[78:79] offset:576
	s_waitcnt lgkmcnt(0)
	v_add_f32_e32 v0, v0, v1
	ds_bpermute_b32 v1, v116, v0
	v_cvt_pk_bf16_f32 v2, v2, v3
	v_cvt_pk_bf16_f32 v3, v4, v5
	global_store_dwordx2 v23, v[2:3], s[6:7] offset:288
	s_and_saveexec_b64 s[54:55], s[0:1]
	s_cbranch_execz .LBB0_1180
	v_readlane_b32 s34, v254, 43
	v_lshlrev_b64 v[2:3], 6, v[16:17]
	v_readlane_b32 s35, v254, 44
	v_lshl_add_u64 v[2:3], s[42:43], 0, v[2:3]
	s_mov_b32 s31, s35
	v_lshl_add_u64 v[2:3], s[52:53], 2, v[2:3]
	s_lshl_b32 s34, s64, 2
	v_writelane_b32 v254, s30, 43
	v_lshl_add_u64 v[2:3], v[2:3], 0, s[34:35]
	s_waitcnt lgkmcnt(0)
	v_add_f32_e32 v0, v0, v1
	v_writelane_b32 v254, s31, 44
	global_store_dword v[2:3], v0, off

.LBB0_1255:
	v_lshl_add_u32 v140, s27, 8, v144
	v_lshrrev_b32_e32 v190, 4, v197
	v_and_b32_e32 v191, 1, v190
	v_lshlrev_b32_e32 v191, 5, v191
	v_lshrrev_b32_e32 v192, 1, v190
	v_lshl_add_u32 v191, v192, 7, v191
	v_add_u32_e32 v192, v140, v191
	v_ashrrev_i32_e32 v193, 31, v192
	v_lshlrev_b64 v[192:193], 6, v[192:193]
	v_lshl_add_u64 v[192:193], s[30:31], 0, v[192:193]
	v_subrev_u32_e32 v193, s40, v192
	global_load_dwordx4 v[172:175], v193, s[40:41]
	global_load_dwordx4 v[176:179], v193, s[40:41] offset:16
	global_load_dwordx4 v[180:183], v193, s[40:41] offset:32
	global_load_dwordx4 v[184:187], v193, s[40:41] offset:48
	global_load_dwordx4 v[226:229], v193, s[40:41] offset:1024
	global_load_dwordx4 v[230:233], v193, s[40:41] offset:1040
	global_load_dwordx4 v[234:237], v193, s[40:41] offset:1056
	global_load_dwordx4 v[238:241], v193, s[40:41] offset:1072
	s_waitcnt vmcnt(0)
	v_add_f32_e32 v172, v172, v173
	v_add_f32_e32 v174, v174, v175
	v_add_f32_e32 v172, v172, v174
	v_add_f32_e32 v176, v176, v177
	v_add_f32_e32 v178, v178, v179
	v_add_f32_e32 v176, v176, v178
	v_add_f32_e32 v180, v180, v181
	v_add_f32_e32 v182, v182, v183
	v_add_f32_e32 v180, v180, v182
	v_add_f32_e32 v184, v184, v185
	v_add_f32_e32 v186, v186, v187
	v_add_f32_e32 v184, v184, v186
	v_add_f32_e32 v172, v172, v176
	v_add_f32_e32 v180, v180, v184
	v_add_f32_e32 v188, v172, v180
	v_add_f32_e32 v226, v226, v227
	v_add_f32_e32 v228, v228, v229
	v_add_f32_e32 v226, v226, v228
	v_add_f32_e32 v230, v230, v231
	v_add_f32_e32 v232, v232, v233
	v_add_f32_e32 v230, v230, v232
	v_add_f32_e32 v234, v234, v235
	v_add_f32_e32 v236, v236, v237
	v_add_f32_e32 v234, v234, v236
	v_add_f32_e32 v238, v238, v239
	v_add_f32_e32 v240, v240, v241
	v_add_f32_e32 v238, v238, v240
	v_add_f32_e32 v226, v226, v230
	v_add_f32_e32 v234, v234, v238
	v_add_f32_e32 v189, v226, v234
	v_fmamk_f32 v188, v188, 0x3a800000, v194
	v_mul_f32_e32 v172, 0x4f800000, v188
	v_cmp_gt_f32_e32 vcc, 0xf800000, v188
	s_nop 1
	v_cndmask_b32_e32 v188, v188, v172, vcc
	v_sqrt_f32_e32 v172, v188
	s_nop 0
	v_add_u32_e32 v173, -1, v172
	v_add_u32_e32 v174, 1, v172
	v_fma_f32 v175, -v173, v172, v188
	v_cmp_ge_f32_e64 s[0:1], 0, v175
	v_fma_f32 v175, -v174, v172, v188
	s_nop 0
	v_cndmask_b32_e64 v172, v172, v173, s[0:1]
	v_cmp_lt_f32_e64 s[0:1], 0, v175
	s_nop 1
	v_cndmask_b32_e64 v172, v172, v174, s[0:1]
	v_mul_f32_e32 v173, 0x37800000, v172
	v_cndmask_b32_e32 v172, v172, v173, vcc
	v_cmp_class_f32_e32 vcc, v188, v195
	s_nop 1
	v_cndmask_b32_e32 v188, v172, v188, vcc
	v_div_scale_f32 v172, s[0:1], v188, v188, 1.0
	v_rcp_f32_e32 v173, v172
	v_div_scale_f32 v174, vcc, 1.0, v188, 1.0
	v_fma_f32 v175, -v172, v173, 1.0
	v_fmac_f32_e32 v173, v175, v173
	v_mul_f32_e32 v175, v174, v173
	v_fma_f32 v242, -v172, v175, v174
	v_fmac_f32_e32 v175, v242, v173
	v_fma_f32 v172, -v172, v175, v174
	v_div_fmas_f32 v172, v172, v173, v175
	v_div_fixup_f32 v188, v172, v188, 1.0
	v_fmamk_f32 v189, v189, 0x3a800000, v194
	v_mul_f32_e32 v176, 0x4f800000, v189
	v_cmp_gt_f32_e32 vcc, 0xf800000, v189
	s_nop 1
	v_cndmask_b32_e32 v189, v189, v176, vcc
	v_sqrt_f32_e32 v176, v189
	s_nop 0
	v_add_u32_e32 v177, -1, v176
	v_add_u32_e32 v178, 1, v176
	v_fma_f32 v179, -v177, v176, v189
	v_cmp_ge_f32_e64 s[0:1], 0, v179
	v_fma_f32 v179, -v178, v176, v189
	s_nop 0
	v_cndmask_b32_e64 v176, v176, v177, s[0:1]
	v_cmp_lt_f32_e64 s[0:1], 0, v179
	s_nop 1
	v_cndmask_b32_e64 v176, v176, v178, s[0:1]
	v_mul_f32_e32 v177, 0x37800000, v176
	v_cndmask_b32_e32 v176, v176, v177, vcc
	v_cmp_class_f32_e32 vcc, v189, v195
	s_nop 1
	v_cndmask_b32_e32 v189, v176, v189, vcc
	v_div_scale_f32 v176, s[0:1], v189, v189, 1.0
	v_rcp_f32_e32 v177, v176
	v_div_scale_f32 v178, vcc, 1.0, v189, 1.0
	v_fma_f32 v179, -v176, v177, 1.0
	v_fmac_f32_e32 v177, v179, v177
	v_mul_f32_e32 v179, v178, v177
	v_fma_f32 v242, -v176, v179, v178
	v_fmac_f32_e32 v179, v242, v177
	v_fma_f32 v176, -v176, v179, v178
	v_div_fmas_f32 v176, v176, v177, v179
	v_div_fixup_f32 v189, v176, v189, 1.0
	v_and_b32_e32 v190, 15, v197
	v_lshlrev_b32_e32 v190, 2, v190
	v_add_u32_e32 v191, 64, v190
	v_add_u32_e32 v192, 128, v190
	v_add_u32_e32 v193, 192, v190
	ds_bpermute_b32 v244, v190, v188
	ds_bpermute_b32 v245, v190, v189
	ds_bpermute_b32 v246, v191, v188
	ds_bpermute_b32 v247, v191, v189
	ds_bpermute_b32 v248, v192, v188
	ds_bpermute_b32 v249, v192, v189
	ds_bpermute_b32 v250, v193, v188
	ds_bpermute_b32 v251, v193, v189
	s_waitcnt lgkmcnt(0)
	v_ashrrev_i32_e32 v141, 31, v140
	v_lshlrev_b64 v[148:149], 6, v[140:141]
	v_lshl_add_u64 v[160:161], s[30:31], 0, v[148:149]
	s_mov_b32 s27, 0xf800000
	v_lshl_or_b32 v142, s26, 7, v146
	v_ashrrev_i32_e32 v143, 31, v142
	s_movk_i32 s26, 0x1600
	v_mov_b32_e32 v200, v202
	s_waitcnt lgkmcnt(0)
	s_nop 0
	s_nop 0
	s_nop 0
	s_nop 0
	s_nop 0
	s_nop 0
	s_nop 0
	s_nop 1
	s_nop 1
	s_nop 0
	v_mov_b32_e32 v148, v244
	v_pk_mul_f32 v[126:127], v[126:127], v[148:149] op_sel_hi:[1,0]
	v_pk_mul_f32 v[118:119], v[118:119], v[148:149] op_sel_hi:[1,0]
	v_mul_f32_e32 v141, 0xbfb8aa3b, v126
	v_exp_f32_e32 v141, v141
	v_pk_mul_f32 v[120:121], v[120:121], v[148:149] op_sel_hi:[1,0]
	v_pk_mul_f32 v[122:123], v[122:123], v[148:149] op_sel_hi:[1,0]
	v_pk_mul_f32 v[114:115], v[114:115], v[148:149] op_sel_hi:[1,0]
	v_add_f32_e32 v141, 1.0, v141
	v_rcp_f32_e32 v150, v141
	v_mul_f32_e32 v141, 0xbfb8aa3b, v127
	v_exp_f32_e32 v141, v141
	v_pk_mul_f32 v[116:117], v[116:117], v[148:149] op_sel_hi:[1,0]
	v_add_f32_e32 v141, 1.0, v141
	v_rcp_f32_e32 v151, v141
	s_nop 0
	v_pk_mul_f32 v[126:127], v[126:127], v[150:151]
	s_nop 0
	v_pk_mul_f32 v[118:119], v[118:119], v[126:127]
	v_pk_mul_f32 v[126:127], v[128:129], v[148:149] op_sel_hi:[1,0]
	s_nop 0
	v_mul_f32_e32 v128, 0xbfb8aa3b, v126
	v_mul_f32_e32 v129, 0xbfb8aa3b, v127
	v_exp_f32_e32 v128, v128
	v_exp_f32_e32 v129, v129
	v_add_f32_e32 v128, 1.0, v128
	v_add_f32_e32 v129, 1.0, v129
	v_rcp_f32_e32 v128, v128
	v_rcp_f32_e32 v129, v129
	s_nop 0
	v_pk_mul_f32 v[126:127], v[126:127], v[128:129]
	s_nop 0
	v_pk_mul_f32 v[120:121], v[120:121], v[126:127]
	v_mul_f32_e32 v126, 0xbfb8aa3b, v122
	v_mul_f32_e32 v127, 0xbfb8aa3b, v123
	v_exp_f32_e32 v126, v126
	v_exp_f32_e32 v127, v127
	v_add_f32_e32 v126, 1.0, v126
	v_add_f32_e32 v127, 1.0, v127
	v_rcp_f32_e32 v126, v126
	v_rcp_f32_e32 v127, v127
	s_nop 0
	v_pk_mul_f32 v[122:123], v[122:123], v[126:127]
	s_nop 0
	v_pk_mul_f32 v[122:123], v[114:115], v[122:123]
	v_pk_mul_f32 v[114:115], v[124:125], v[148:149] op_sel_hi:[1,0]
	s_nop 0
	v_mul_f32_e32 v124, 0xbfb8aa3b, v114
	v_mul_f32_e32 v125, 0xbfb8aa3b, v115
	v_exp_f32_e32 v124, v124
	v_exp_f32_e32 v125, v125
	v_add_f32_e32 v124, 1.0, v124
	v_add_f32_e32 v125, 1.0, v125
	v_rcp_f32_e32 v124, v124
	v_rcp_f32_e32 v125, v125
	s_nop 0
	v_pk_mul_f32 v[114:115], v[114:115], v[124:125]
	s_nop 0
	v_pk_mul_f32 v[124:125], v[116:117], v[114:115]
	v_cvt_pk_bf16_f32 v114, v118, v119
	v_mov_b64_e32 v[118:119], s[6:7]
	v_cvt_pk_bf16_f32 v115, v120, v121
	v_cvt_pk_bf16_f32 v116, v122, v123
	v_mad_i64_i32 v[122:123], s[0:1], v140, s26, v[118:119]
	v_lshlrev_b64 v[120:121], 1, v[142:143]
	v_cvt_pk_bf16_f32 v117, v124, v125
	v_lshl_add_u64 v[122:123], v[122:123], 0, v[120:121]
	v_subrev_u32_e32 v123, s40, v122
	global_store_dwordx4 v123, v[114:117], s[40:41]
	s_nop 1
	v_or_b32_e32 v114, 16, v140
	v_ashrrev_i32_e32 v115, 31, v114
	v_lshlrev_b64 v[116:117], 6, v[114:115]
	v_lshl_add_u64 v[116:117], s[30:31], 0, v[116:117]
	s_waitcnt lgkmcnt(0)
	s_nop 0
	s_nop 0
	s_nop 0
	s_nop 0
	s_nop 0
	s_nop 0
	s_nop 1
	s_nop 1
	s_nop 0
	v_mov_b32_e32 v116, v245
	v_pk_mul_f32 v[110:111], v[110:111], v[116:117] op_sel_hi:[1,0]
	v_pk_mul_f32 v[102:103], v[102:103], v[116:117] op_sel_hi:[1,0]
	v_mul_f32_e32 v115, 0xbfb8aa3b, v110
	v_exp_f32_e32 v115, v115
	v_pk_mul_f32 v[104:105], v[104:105], v[116:117] op_sel_hi:[1,0]
	v_pk_mul_f32 v[106:107], v[106:107], v[116:117] op_sel_hi:[1,0]
	v_pk_mul_f32 v[98:99], v[98:99], v[116:117] op_sel_hi:[1,0]
	v_add_f32_e32 v115, 1.0, v115
	v_rcp_f32_e32 v122, v115
	v_mul_f32_e32 v115, 0xbfb8aa3b, v111
	v_exp_f32_e32 v115, v115
	v_pk_mul_f32 v[100:101], v[100:101], v[116:117] op_sel_hi:[1,0]
	v_add_f32_e32 v115, 1.0, v115
	v_rcp_f32_e32 v123, v115
	s_nop 0
	v_pk_mul_f32 v[110:111], v[110:111], v[122:123]
	s_nop 0
	v_pk_mul_f32 v[102:103], v[102:103], v[110:111]
	v_pk_mul_f32 v[110:111], v[112:113], v[116:117] op_sel_hi:[1,0]
	s_nop 0
	v_mul_f32_e32 v112, 0xbfb8aa3b, v110
	v_mul_f32_e32 v113, 0xbfb8aa3b, v111
	v_exp_f32_e32 v112, v112
	v_exp_f32_e32 v113, v113
	v_add_f32_e32 v112, 1.0, v112
	v_add_f32_e32 v113, 1.0, v113
	v_rcp_f32_e32 v112, v112
	v_rcp_f32_e32 v113, v113
	s_nop 0
	v_pk_mul_f32 v[110:111], v[110:111], v[112:113]
	s_nop 0
	v_pk_mul_f32 v[104:105], v[104:105], v[110:111]
	v_mul_f32_e32 v110, 0xbfb8aa3b, v106
	v_mul_f32_e32 v111, 0xbfb8aa3b, v107
	v_exp_f32_e32 v110, v110
	v_exp_f32_e32 v111, v111
	v_add_f32_e32 v110, 1.0, v110
	v_add_f32_e32 v111, 1.0, v111
	v_rcp_f32_e32 v110, v110
	v_rcp_f32_e32 v111, v111
	s_nop 0
	v_pk_mul_f32 v[106:107], v[106:107], v[110:111]
	s_nop 0
	v_pk_mul_f32 v[106:107], v[98:99], v[106:107]
	v_pk_mul_f32 v[98:99], v[108:109], v[116:117] op_sel_hi:[1,0]
	s_nop 0
	v_mul_f32_e32 v108, 0xbfb8aa3b, v98
	v_mul_f32_e32 v109, 0xbfb8aa3b, v99
	v_exp_f32_e32 v108, v108
	v_exp_f32_e32 v109, v109
	v_add_f32_e32 v108, 1.0, v108
	v_add_f32_e32 v109, 1.0, v109
	v_rcp_f32_e32 v108, v108
	v_rcp_f32_e32 v109, v109
	s_nop 0
	v_pk_mul_f32 v[98:99], v[98:99], v[108:109]
	s_nop 0
	v_pk_mul_f32 v[108:109], v[100:101], v[98:99]
	v_cvt_pk_bf16_f32 v98, v102, v103
	v_mad_i64_i32 v[102:103], s[0:1], v114, s26, v[118:119]
	v_cvt_pk_bf16_f32 v99, v104, v105
	v_cvt_pk_bf16_f32 v100, v106, v107
	v_cvt_pk_bf16_f32 v101, v108, v109
	v_lshl_add_u64 v[102:103], v[102:103], 0, v[120:121]
	v_subrev_u32_e32 v103, s40, v102
	global_store_dwordx4 v103, v[98:101], s[40:41]
	s_nop 1
	v_or_b32_e32 v98, 32, v140
	v_ashrrev_i32_e32 v99, 31, v98
	v_lshlrev_b64 v[100:101], 6, v[98:99]
	v_lshl_add_u64 v[100:101], s[30:31], 0, v[100:101]
	s_waitcnt lgkmcnt(0)
	s_nop 0
	s_nop 0
	s_nop 0
	s_nop 0
	s_nop 0
	s_nop 0
	s_nop 1
	s_nop 1
	s_nop 0
	v_mov_b32_e32 v100, v246
	v_pk_mul_f32 v[94:95], v[94:95], v[100:101] op_sel_hi:[1,0]
	v_pk_mul_f32 v[86:87], v[86:87], v[100:101] op_sel_hi:[1,0]
	v_mul_f32_e32 v99, 0xbfb8aa3b, v94
	v_exp_f32_e32 v99, v99
	v_pk_mul_f32 v[88:89], v[88:89], v[100:101] op_sel_hi:[1,0]
	v_pk_mul_f32 v[90:91], v[90:91], v[100:101] op_sel_hi:[1,0]
	v_pk_mul_f32 v[82:83], v[82:83], v[100:101] op_sel_hi:[1,0]
	v_add_f32_e32 v99, 1.0, v99
	v_rcp_f32_e32 v102, v99
	v_mul_f32_e32 v99, 0xbfb8aa3b, v95
	v_exp_f32_e32 v99, v99
	v_pk_mul_f32 v[84:85], v[84:85], v[100:101] op_sel_hi:[1,0]
	v_add_f32_e32 v99, 1.0, v99
	v_rcp_f32_e32 v103, v99
	s_nop 0
	v_pk_mul_f32 v[94:95], v[94:95], v[102:103]
	s_nop 0
	v_pk_mul_f32 v[86:87], v[86:87], v[94:95]
	v_pk_mul_f32 v[94:95], v[96:97], v[100:101] op_sel_hi:[1,0]
	s_nop 0
	v_mul_f32_e32 v96, 0xbfb8aa3b, v94
	v_mul_f32_e32 v97, 0xbfb8aa3b, v95
	v_exp_f32_e32 v96, v96
	v_exp_f32_e32 v97, v97
	v_add_f32_e32 v96, 1.0, v96
	v_add_f32_e32 v97, 1.0, v97
	v_rcp_f32_e32 v96, v96
	v_rcp_f32_e32 v97, v97
	s_nop 0
	v_pk_mul_f32 v[94:95], v[94:95], v[96:97]
	s_nop 0
	v_pk_mul_f32 v[88:89], v[88:89], v[94:95]
	v_mul_f32_e32 v94, 0xbfb8aa3b, v90
	v_mul_f32_e32 v95, 0xbfb8aa3b, v91
	v_exp_f32_e32 v94, v94
	v_exp_f32_e32 v95, v95
	v_add_f32_e32 v94, 1.0, v94
	v_add_f32_e32 v95, 1.0, v95
	v_rcp_f32_e32 v94, v94
	v_rcp_f32_e32 v95, v95
	s_nop 0
	v_pk_mul_f32 v[90:91], v[90:91], v[94:95]
	s_nop 0
	v_pk_mul_f32 v[90:91], v[82:83], v[90:91]
	v_pk_mul_f32 v[82:83], v[92:93], v[100:101] op_sel_hi:[1,0]
	s_nop 0
	v_mul_f32_e32 v92, 0xbfb8aa3b, v82
	v_mul_f32_e32 v93, 0xbfb8aa3b, v83
	v_exp_f32_e32 v92, v92
	v_exp_f32_e32 v93, v93
	v_add_f32_e32 v92, 1.0, v92
	v_add_f32_e32 v93, 1.0, v93
	v_rcp_f32_e32 v92, v92
	v_rcp_f32_e32 v93, v93
	s_nop 0
	v_pk_mul_f32 v[82:83], v[82:83], v[92:93]
	s_nop 0
	v_pk_mul_f32 v[92:93], v[84:85], v[82:83]
	v_cvt_pk_bf16_f32 v82, v86, v87
	v_mad_i64_i32 v[86:87], s[0:1], v98, s26, v[118:119]
	v_cvt_pk_bf16_f32 v83, v88, v89
	v_cvt_pk_bf16_f32 v84, v90, v91
	v_cvt_pk_bf16_f32 v85, v92, v93
	v_lshl_add_u64 v[86:87], v[86:87], 0, v[120:121]
	v_subrev_u32_e32 v87, s40, v86
	global_store_dwordx4 v87, v[82:85], s[40:41]
	s_nop 1
	v_or_b32_e32 v82, 48, v140
	v_ashrrev_i32_e32 v83, 31, v82
	v_lshlrev_b64 v[84:85], 6, v[82:83]
	v_lshl_add_u64 v[84:85], s[30:31], 0, v[84:85]
	s_waitcnt lgkmcnt(0)
	s_nop 0
	s_nop 0
	s_nop 0
	s_nop 0
	s_nop 0
	s_nop 0
	s_nop 1
	s_nop 1
	s_nop 0
	v_mov_b32_e32 v84, v247
	v_pk_mul_f32 v[78:79], v[78:79], v[84:85] op_sel_hi:[1,0]
	v_pk_mul_f32 v[70:71], v[70:71], v[84:85] op_sel_hi:[1,0]
	v_mul_f32_e32 v83, 0xbfb8aa3b, v78
	v_exp_f32_e32 v83, v83
	v_pk_mul_f32 v[72:73], v[72:73], v[84:85] op_sel_hi:[1,0]
	v_pk_mul_f32 v[74:75], v[74:75], v[84:85] op_sel_hi:[1,0]
	v_pk_mul_f32 v[66:67], v[66:67], v[84:85] op_sel_hi:[1,0]
	v_add_f32_e32 v83, 1.0, v83
	v_rcp_f32_e32 v86, v83
	v_mul_f32_e32 v83, 0xbfb8aa3b, v79
	v_exp_f32_e32 v83, v83
	v_pk_mul_f32 v[68:69], v[68:69], v[84:85] op_sel_hi:[1,0]
	v_add_f32_e32 v83, 1.0, v83
	v_rcp_f32_e32 v87, v83
	s_nop 0
	v_pk_mul_f32 v[78:79], v[78:79], v[86:87]
	s_nop 0
	v_pk_mul_f32 v[70:71], v[70:71], v[78:79]
	v_pk_mul_f32 v[78:79], v[80:81], v[84:85] op_sel_hi:[1,0]
	s_nop 0
	v_mul_f32_e32 v80, 0xbfb8aa3b, v78
	v_mul_f32_e32 v81, 0xbfb8aa3b, v79
	v_exp_f32_e32 v80, v80
	v_exp_f32_e32 v81, v81
	v_add_f32_e32 v80, 1.0, v80
	v_add_f32_e32 v81, 1.0, v81
	v_rcp_f32_e32 v80, v80
	v_rcp_f32_e32 v81, v81
	s_nop 0
	v_pk_mul_f32 v[78:79], v[78:79], v[80:81]
	s_nop 0
	v_pk_mul_f32 v[72:73], v[72:73], v[78:79]
	v_mul_f32_e32 v78, 0xbfb8aa3b, v74
	v_mul_f32_e32 v79, 0xbfb8aa3b, v75
	v_exp_f32_e32 v78, v78
	v_exp_f32_e32 v79, v79
	v_add_f32_e32 v78, 1.0, v78
	v_add_f32_e32 v79, 1.0, v79
	v_rcp_f32_e32 v78, v78
	v_rcp_f32_e32 v79, v79
	s_nop 0
	v_pk_mul_f32 v[74:75], v[74:75], v[78:79]
	s_nop 0
	v_pk_mul_f32 v[74:75], v[66:67], v[74:75]
	v_pk_mul_f32 v[66:67], v[76:77], v[84:85] op_sel_hi:[1,0]
	s_nop 0
	v_mul_f32_e32 v76, 0xbfb8aa3b, v66
	v_mul_f32_e32 v77, 0xbfb8aa3b, v67
	v_exp_f32_e32 v76, v76
	v_exp_f32_e32 v77, v77
	v_add_f32_e32 v76, 1.0, v76
	v_add_f32_e32 v77, 1.0, v77
	v_rcp_f32_e32 v76, v76
	v_rcp_f32_e32 v77, v77
	s_nop 0
	v_pk_mul_f32 v[66:67], v[66:67], v[76:77]
	s_nop 0
	v_pk_mul_f32 v[76:77], v[68:69], v[66:67]
	v_cvt_pk_bf16_f32 v66, v70, v71
	v_mad_i64_i32 v[70:71], s[0:1], v82, s26, v[118:119]
	v_cvt_pk_bf16_f32 v67, v72, v73
	v_cvt_pk_bf16_f32 v68, v74, v75
	v_cvt_pk_bf16_f32 v69, v76, v77
	v_lshl_add_u64 v[70:71], v[70:71], 0, v[120:121]
	v_subrev_u32_e32 v71, s40, v70
	global_store_dwordx4 v71, v[66:69], s[40:41]
	s_nop 1
	v_add_u32_e32 v66, 0x80, v140
	v_ashrrev_i32_e32 v67, 31, v66
	v_lshlrev_b64 v[68:69], 6, v[66:67]
	v_lshl_add_u64 v[68:69], s[30:31], 0, v[68:69]
	s_waitcnt lgkmcnt(0)
	s_nop 0
	s_nop 0
	s_nop 0
	s_nop 0
	s_nop 0
	s_nop 0
	s_nop 1
	s_nop 1
	s_nop 0
	v_mov_b32_e32 v68, v248
	v_pk_mul_f32 v[60:61], v[60:61], v[68:69] op_sel_hi:[1,0]
	v_pk_mul_f32 v[52:53], v[52:53], v[68:69] op_sel_hi:[1,0]
	v_mul_f32_e32 v67, 0xbfb8aa3b, v60
	v_exp_f32_e32 v67, v67
	v_pk_mul_f32 v[54:55], v[54:55], v[68:69] op_sel_hi:[1,0]
	v_pk_mul_f32 v[56:57], v[56:57], v[68:69] op_sel_hi:[1,0]
	v_pk_mul_f32 v[48:49], v[48:49], v[68:69] op_sel_hi:[1,0]
	v_add_f32_e32 v67, 1.0, v67
	v_rcp_f32_e32 v70, v67
	v_mul_f32_e32 v67, 0xbfb8aa3b, v61
	v_exp_f32_e32 v67, v67
	v_pk_mul_f32 v[50:51], v[50:51], v[68:69] op_sel_hi:[1,0]
	v_add_f32_e32 v67, 1.0, v67
	v_rcp_f32_e32 v71, v67
	s_nop 0
	v_pk_mul_f32 v[60:61], v[60:61], v[70:71]
	s_nop 0
	v_pk_mul_f32 v[52:53], v[52:53], v[60:61]
	v_pk_mul_f32 v[60:61], v[62:63], v[68:69] op_sel_hi:[1,0]
	s_nop 0
	v_mul_f32_e32 v62, 0xbfb8aa3b, v60
	v_mul_f32_e32 v63, 0xbfb8aa3b, v61
	v_exp_f32_e32 v62, v62
	v_exp_f32_e32 v63, v63
	v_add_f32_e32 v62, 1.0, v62
	v_add_f32_e32 v63, 1.0, v63
	v_rcp_f32_e32 v62, v62
	v_rcp_f32_e32 v63, v63
	s_nop 0
	v_pk_mul_f32 v[60:61], v[60:61], v[62:63]
	s_nop 0
	v_pk_mul_f32 v[54:55], v[54:55], v[60:61]
	v_mul_f32_e32 v60, 0xbfb8aa3b, v56
	v_mul_f32_e32 v61, 0xbfb8aa3b, v57
	v_exp_f32_e32 v60, v60
	v_exp_f32_e32 v61, v61
	v_add_f32_e32 v60, 1.0, v60
	v_add_f32_e32 v61, 1.0, v61
	v_rcp_f32_e32 v60, v60
	v_rcp_f32_e32 v61, v61
	s_nop 0
	v_pk_mul_f32 v[56:57], v[56:57], v[60:61]
	s_nop 0
	v_pk_mul_f32 v[56:57], v[48:49], v[56:57]
	v_pk_mul_f32 v[48:49], v[58:59], v[68:69] op_sel_hi:[1,0]
	s_nop 0
	v_mul_f32_e32 v58, 0xbfb8aa3b, v48
	v_mul_f32_e32 v59, 0xbfb8aa3b, v49
	v_exp_f32_e32 v58, v58
	v_exp_f32_e32 v59, v59
	v_add_f32_e32 v58, 1.0, v58
	v_add_f32_e32 v59, 1.0, v59
	v_rcp_f32_e32 v58, v58
	v_rcp_f32_e32 v59, v59
	s_nop 0
	v_pk_mul_f32 v[48:49], v[48:49], v[58:59]
	s_nop 0
	v_pk_mul_f32 v[58:59], v[50:51], v[48:49]
	v_cvt_pk_bf16_f32 v48, v52, v53
	v_mad_i64_i32 v[52:53], s[0:1], v66, s26, v[118:119]
	v_cvt_pk_bf16_f32 v49, v54, v55
	v_cvt_pk_bf16_f32 v50, v56, v57
	v_cvt_pk_bf16_f32 v51, v58, v59
	v_lshl_add_u64 v[52:53], v[52:53], 0, v[120:121]
	v_subrev_u32_e32 v53, s40, v52
	global_store_dwordx4 v53, v[48:51], s[40:41]
	s_nop 1
	v_add_u32_e32 v48, 0x90, v140
	v_ashrrev_i32_e32 v49, 31, v48
	v_lshlrev_b64 v[50:51], 6, v[48:49]
	v_lshl_add_u64 v[50:51], s[30:31], 0, v[50:51]
	s_waitcnt lgkmcnt(0)
	s_nop 0
	s_nop 0
	s_nop 0
	s_nop 0
	s_nop 0
	s_nop 0
	s_nop 1
	s_nop 1
	s_nop 0
	v_mov_b32_e32 v50, v249
	v_pk_mul_f32 v[44:45], v[44:45], v[50:51] op_sel_hi:[1,0]
	v_pk_mul_f32 v[36:37], v[36:37], v[50:51] op_sel_hi:[1,0]
	v_mul_f32_e32 v49, 0xbfb8aa3b, v44
	v_exp_f32_e32 v49, v49
	v_pk_mul_f32 v[38:39], v[38:39], v[50:51] op_sel_hi:[1,0]
	v_pk_mul_f32 v[40:41], v[40:41], v[50:51] op_sel_hi:[1,0]
	v_pk_mul_f32 v[32:33], v[32:33], v[50:51] op_sel_hi:[1,0]
	v_add_f32_e32 v49, 1.0, v49
	v_rcp_f32_e32 v52, v49
	v_mul_f32_e32 v49, 0xbfb8aa3b, v45
	v_exp_f32_e32 v49, v49
	v_pk_mul_f32 v[34:35], v[34:35], v[50:51] op_sel_hi:[1,0]
	v_add_f32_e32 v49, 1.0, v49
	v_rcp_f32_e32 v53, v49
	s_nop 0
	v_pk_mul_f32 v[44:45], v[44:45], v[52:53]
	s_nop 0
	v_pk_mul_f32 v[36:37], v[36:37], v[44:45]
	v_pk_mul_f32 v[44:45], v[46:47], v[50:51] op_sel_hi:[1,0]
	s_nop 0
	v_mul_f32_e32 v46, 0xbfb8aa3b, v44
	v_mul_f32_e32 v47, 0xbfb8aa3b, v45
	v_exp_f32_e32 v46, v46
	v_exp_f32_e32 v47, v47
	v_add_f32_e32 v46, 1.0, v46
	v_add_f32_e32 v47, 1.0, v47
	v_rcp_f32_e32 v46, v46
	v_rcp_f32_e32 v47, v47
	s_nop 0
	v_pk_mul_f32 v[44:45], v[44:45], v[46:47]
	s_nop 0
	v_pk_mul_f32 v[38:39], v[38:39], v[44:45]
	v_mul_f32_e32 v44, 0xbfb8aa3b, v40
	v_mul_f32_e32 v45, 0xbfb8aa3b, v41
	v_exp_f32_e32 v44, v44
	v_exp_f32_e32 v45, v45
	v_add_f32_e32 v44, 1.0, v44
	v_add_f32_e32 v45, 1.0, v45
	v_rcp_f32_e32 v44, v44
	v_rcp_f32_e32 v45, v45
	s_nop 0
	v_pk_mul_f32 v[40:41], v[40:41], v[44:45]
	s_nop 0
	v_pk_mul_f32 v[40:41], v[32:33], v[40:41]
	v_pk_mul_f32 v[32:33], v[42:43], v[50:51] op_sel_hi:[1,0]
	s_nop 0
	v_mul_f32_e32 v42, 0xbfb8aa3b, v32
	v_mul_f32_e32 v43, 0xbfb8aa3b, v33
	v_exp_f32_e32 v42, v42
	v_exp_f32_e32 v43, v43
	v_add_f32_e32 v42, 1.0, v42
	v_add_f32_e32 v43, 1.0, v43
	v_rcp_f32_e32 v42, v42
	v_rcp_f32_e32 v43, v43
	s_nop 0
	v_pk_mul_f32 v[32:33], v[32:33], v[42:43]
	s_nop 0
	v_pk_mul_f32 v[42:43], v[34:35], v[32:33]
	v_cvt_pk_bf16_f32 v32, v36, v37
	v_mad_i64_i32 v[36:37], s[0:1], v48, s26, v[118:119]
	v_cvt_pk_bf16_f32 v33, v38, v39
	v_cvt_pk_bf16_f32 v34, v40, v41
	v_cvt_pk_bf16_f32 v35, v42, v43
	v_lshl_add_u64 v[36:37], v[36:37], 0, v[120:121]
	v_subrev_u32_e32 v37, s40, v36
	global_store_dwordx4 v37, v[32:35], s[40:41]
	s_nop 1
	v_add_u32_e32 v32, 0xa0, v140
	v_ashrrev_i32_e32 v33, 31, v32
	v_lshlrev_b64 v[34:35], 6, v[32:33]
	v_lshl_add_u64 v[34:35], s[30:31], 0, v[34:35]
	s_waitcnt lgkmcnt(0)
	s_nop 0
	s_nop 0
	s_nop 0
	s_nop 0
	s_nop 0
	s_nop 0
	s_nop 1
	s_nop 1
	s_nop 0
	v_mov_b32_e32 v34, v250
	v_pk_mul_f32 v[28:29], v[28:29], v[34:35] op_sel_hi:[1,0]
	v_pk_mul_f32 v[20:21], v[20:21], v[34:35] op_sel_hi:[1,0]
	v_mul_f32_e32 v33, 0xbfb8aa3b, v28
	v_exp_f32_e32 v33, v33
	v_pk_mul_f32 v[22:23], v[22:23], v[34:35] op_sel_hi:[1,0]
	v_pk_mul_f32 v[24:25], v[24:25], v[34:35] op_sel_hi:[1,0]
	v_pk_mul_f32 v[16:17], v[16:17], v[34:35] op_sel_hi:[1,0]
	v_add_f32_e32 v33, 1.0, v33
	v_rcp_f32_e32 v36, v33
	v_mul_f32_e32 v33, 0xbfb8aa3b, v29
	v_exp_f32_e32 v33, v33
	v_pk_mul_f32 v[18:19], v[18:19], v[34:35] op_sel_hi:[1,0]
	v_add_f32_e32 v33, 1.0, v33
	v_rcp_f32_e32 v37, v33
	s_nop 0
	v_pk_mul_f32 v[28:29], v[28:29], v[36:37]
	s_nop 0
	v_pk_mul_f32 v[20:21], v[20:21], v[28:29]
	v_pk_mul_f32 v[28:29], v[30:31], v[34:35] op_sel_hi:[1,0]
	s_nop 0
	v_mul_f32_e32 v30, 0xbfb8aa3b, v28
	v_mul_f32_e32 v31, 0xbfb8aa3b, v29
	v_exp_f32_e32 v30, v30
	v_exp_f32_e32 v31, v31
	v_add_f32_e32 v30, 1.0, v30
	v_add_f32_e32 v31, 1.0, v31
	v_rcp_f32_e32 v30, v30
	v_rcp_f32_e32 v31, v31
	s_nop 0
	v_pk_mul_f32 v[28:29], v[28:29], v[30:31]
	s_nop 0
	v_pk_mul_f32 v[22:23], v[22:23], v[28:29]
	v_mul_f32_e32 v28, 0xbfb8aa3b, v24
	v_mul_f32_e32 v29, 0xbfb8aa3b, v25
	v_exp_f32_e32 v28, v28
	v_exp_f32_e32 v29, v29
	v_add_f32_e32 v28, 1.0, v28
	v_add_f32_e32 v29, 1.0, v29
	v_rcp_f32_e32 v28, v28
	v_rcp_f32_e32 v29, v29
	s_nop 0
	v_pk_mul_f32 v[24:25], v[24:25], v[28:29]
	s_nop 0
	v_pk_mul_f32 v[24:25], v[16:17], v[24:25]
	v_pk_mul_f32 v[16:17], v[26:27], v[34:35] op_sel_hi:[1,0]
	s_nop 0
	v_mul_f32_e32 v26, 0xbfb8aa3b, v16
	v_mul_f32_e32 v27, 0xbfb8aa3b, v17
	v_exp_f32_e32 v26, v26
	v_exp_f32_e32 v27, v27
	v_add_f32_e32 v26, 1.0, v26
	v_add_f32_e32 v27, 1.0, v27
	v_rcp_f32_e32 v26, v26
	v_rcp_f32_e32 v27, v27
	s_nop 0
	v_pk_mul_f32 v[16:17], v[16:17], v[26:27]
	s_nop 0
	v_pk_mul_f32 v[26:27], v[18:19], v[16:17]
	v_cvt_pk_bf16_f32 v16, v20, v21
	v_mad_i64_i32 v[20:21], s[0:1], v32, s26, v[118:119]
	v_cvt_pk_bf16_f32 v17, v22, v23
	v_cvt_pk_bf16_f32 v18, v24, v25
	v_cvt_pk_bf16_f32 v19, v26, v27
	v_lshl_add_u64 v[20:21], v[20:21], 0, v[120:121]
	v_subrev_u32_e32 v21, s40, v20
	global_store_dwordx4 v21, v[16:19], s[40:41]
	s_nop 1
	v_add_u32_e32 v16, 0xb0, v140
	v_ashrrev_i32_e32 v17, 31, v16
	v_lshlrev_b64 v[18:19], 6, v[16:17]
	v_lshl_add_u64 v[18:19], s[30:31], 0, v[18:19]
	s_waitcnt lgkmcnt(0)
	s_nop 0
	s_nop 0
	s_nop 0
	s_nop 0
	s_nop 0
	s_nop 0
	s_nop 1
	s_nop 1
	s_nop 0
	v_mov_b32_e32 v18, v251
	v_pk_mul_f32 v[12:13], v[12:13], v[18:19] op_sel_hi:[1,0]
	v_pk_mul_f32 v[4:5], v[4:5], v[18:19] op_sel_hi:[1,0]
	v_mul_f32_e32 v17, 0xbfb8aa3b, v12
	v_exp_f32_e32 v17, v17
	v_pk_mul_f32 v[6:7], v[6:7], v[18:19] op_sel_hi:[1,0]
	v_pk_mul_f32 v[8:9], v[8:9], v[18:19] op_sel_hi:[1,0]
	v_pk_mul_f32 v[0:1], v[0:1], v[18:19] op_sel_hi:[1,0]
	v_add_f32_e32 v17, 1.0, v17
	v_rcp_f32_e32 v20, v17
	v_mul_f32_e32 v17, 0xbfb8aa3b, v13
	v_exp_f32_e32 v17, v17
	v_pk_mul_f32 v[2:3], v[2:3], v[18:19] op_sel_hi:[1,0]
	s_andn2_b64 vcc, exec, s[38:39]
	v_add_f32_e32 v17, 1.0, v17
	v_rcp_f32_e32 v21, v17
	s_nop 0
	v_pk_mul_f32 v[12:13], v[12:13], v[20:21]
	s_nop 0
	v_pk_mul_f32 v[4:5], v[4:5], v[12:13]
	v_pk_mul_f32 v[12:13], v[14:15], v[18:19] op_sel_hi:[1,0]
	s_nop 0
	v_mul_f32_e32 v14, 0xbfb8aa3b, v12
	v_mul_f32_e32 v15, 0xbfb8aa3b, v13
	v_exp_f32_e32 v14, v14
	v_exp_f32_e32 v15, v15
	v_add_f32_e32 v14, 1.0, v14
	v_add_f32_e32 v15, 1.0, v15
	v_rcp_f32_e32 v14, v14
	v_rcp_f32_e32 v15, v15
	s_nop 0
	v_pk_mul_f32 v[12:13], v[12:13], v[14:15]
	s_nop 0
	v_pk_mul_f32 v[6:7], v[6:7], v[12:13]
	v_mul_f32_e32 v12, 0xbfb8aa3b, v8
	v_mul_f32_e32 v13, 0xbfb8aa3b, v9
	v_exp_f32_e32 v12, v12
	v_exp_f32_e32 v13, v13
	v_add_f32_e32 v12, 1.0, v12
	v_add_f32_e32 v13, 1.0, v13
	v_rcp_f32_e32 v12, v12
	v_rcp_f32_e32 v13, v13
	s_nop 0
	v_pk_mul_f32 v[8:9], v[8:9], v[12:13]
	s_nop 0
	v_pk_mul_f32 v[8:9], v[0:1], v[8:9]
	v_pk_mul_f32 v[0:1], v[10:11], v[18:19] op_sel_hi:[1,0]
	s_nop 0
	v_mul_f32_e32 v10, 0xbfb8aa3b, v0
	v_mul_f32_e32 v11, 0xbfb8aa3b, v1
	v_exp_f32_e32 v10, v10
	v_exp_f32_e32 v11, v11
	v_add_f32_e32 v10, 1.0, v10
	v_add_f32_e32 v11, 1.0, v11
	v_rcp_f32_e32 v10, v10
	v_rcp_f32_e32 v11, v11
	s_nop 0
	v_pk_mul_f32 v[0:1], v[0:1], v[10:11]
	s_nop 0
	v_pk_mul_f32 v[10:11], v[2:3], v[0:1]
	v_cvt_pk_bf16_f32 v0, v4, v5
	v_mad_i64_i32 v[4:5], s[0:1], v16, s26, v[118:119]
	v_cvt_pk_bf16_f32 v1, v6, v7
	v_cvt_pk_bf16_f32 v2, v8, v9
	v_cvt_pk_bf16_f32 v3, v10, v11
	v_lshl_add_u64 v[4:5], v[4:5], 0, v[120:121]
	v_subrev_u32_e32 v5, s40, v4
	s_mov_b64 s[0:1], -1
	global_store_dwordx4 v5, v[0:3], s[40:41]
	s_cbranch_vccnz .LBB0_1248
	s_andn2_b64 vcc, exec, s[4:5]
	s_cbranch_vccnz .LBB0_1247
	s_barrier
	s_branch .LBB0_1247

.LBB0_1685:
	v_lshl_add_u32 v138, s27, 8, v144
	v_lshl_or_b32 v136, s26, 8, v146
	v_ashrrev_i32_e32 v139, 31, v138
	v_ashrrev_i32_e32 v137, 31, v136
	v_lshlrev_b64 v[140:141], 10, v[138:139]
	v_readlane_b32 s84, v254, 45
	v_lshl_add_u64 v[142:143], v[140:141], 0, v[136:137]
	v_readlane_b32 s90, v254, 51
	v_readlane_b32 s91, v254, 52
	s_lshl_b32 s50, s26, 2
	v_cndmask_b32_e64 v152, 0, 1, s[44:45]
	v_lshlrev_b32_e32 v141, 2, v142
	global_load_dwordx4 v[148:151], v141, s[90:91]
	s_ashr_i32 s51, s50, 31
	v_cmp_ne_u32_e64 s[38:39], 1, v152
	s_andn2_b64 vcc, exec, s[44:45]
	v_readlane_b32 s33, v255, 5
	v_readlane_b32 s85, v254, 46
	v_readlane_b32 s86, v254, 47
	v_readlane_b32 s87, v254, 48
	v_readlane_b32 s88, v254, 49
	v_readlane_b32 s89, v254, 50
	s_waitcnt vmcnt(0)
	v_pk_add_f32 v[128:129], v[128:129], v[150:151]
	v_pk_add_f32 v[126:127], v[126:127], v[148:149]
	global_store_dwordx4 v141, v[126:129], s[90:91]
	s_cbranch_vccnz .LBB0_1728
	v_cvt_pk_bf16_f32 v148, v126, v127
	v_mul_f32_e32 v127, v127, v127
	v_cvt_pk_bf16_f32 v149, v128, v129
	v_lshlrev_b32_e32 v143, 1, v142
	v_fmac_f32_e32 v127, v126, v126
	v_mul_f32_e32 v126, v129, v129
	global_store_dwordx2 v143, v[148:149], s[4:5]
	v_fmac_f32_e32 v126, v128, v128
	v_add_f32_e32 v150, v127, v126
	global_load_dwordx4 v[126:129], v141, s[90:91] offset:64
	s_waitcnt vmcnt(0)
	v_pk_add_f32 v[128:129], v[124:125], v[128:129]
	v_pk_add_f32 v[126:127], v[122:123], v[126:127]
	global_store_dwordx4 v141, v[126:129], s[90:91] offset:64
	v_cvt_pk_bf16_f32 v148, v126, v127
	v_cvt_pk_bf16_f32 v149, v128, v129
	v_mul_f32_e32 v127, v127, v127
	v_fmac_f32_e32 v127, v126, v126
	v_mul_f32_e32 v126, v129, v129
	v_fmac_f32_e32 v126, v128, v128
	global_store_dwordx2 v143, v[148:149], s[4:5] offset:32
	v_add_f32_e32 v126, v127, v126
	v_add_f32_e32 v150, v150, v126
	global_load_dwordx4 v[126:129], v141, s[90:91] offset:512
	s_waitcnt vmcnt(0)
	v_pk_add_f32 v[128:129], v[120:121], v[128:129]
	v_pk_add_f32 v[126:127], v[118:119], v[126:127]
	global_store_dwordx4 v141, v[126:129], s[90:91] offset:512
	v_cvt_pk_bf16_f32 v148, v126, v127
	v_cvt_pk_bf16_f32 v149, v128, v129
	v_mul_f32_e32 v127, v127, v127
	v_fmac_f32_e32 v127, v126, v126
	v_mul_f32_e32 v126, v129, v129
	v_fmac_f32_e32 v126, v128, v128
	global_store_dwordx2 v143, v[148:149], s[4:5] offset:256
	v_add_f32_e32 v126, v127, v126
	v_add_f32_e32 v150, v150, v126
	global_load_dwordx4 v[126:129], v141, s[90:91] offset:576
	s_waitcnt vmcnt(0)
	v_pk_add_f32 v[128:129], v[116:117], v[128:129]
	v_pk_add_f32 v[126:127], v[114:115], v[126:127]
	global_store_dwordx4 v141, v[126:129], s[90:91] offset:576
	v_cvt_pk_bf16_f32 v148, v126, v127
	v_cvt_pk_bf16_f32 v149, v128, v129
	v_mul_f32_e32 v127, v127, v127
	v_fmac_f32_e32 v127, v126, v126
	v_mul_f32_e32 v126, v129, v129
	v_fmac_f32_e32 v126, v128, v128
	v_and_b32_e32 v128, 64, v197
	v_add_f32_e32 v126, v127, v126
	v_xor_b32_e32 v127, 16, v197
	v_add_u32_e32 v128, 64, v128
	v_cmp_lt_i32_e32 vcc, v127, v128
	v_add_f32_e32 v126, v150, v126
	global_store_dwordx2 v143, v[148:149], s[4:5] offset:288
	v_cndmask_b32_e32 v127, v197, v127, vcc
	v_lshlrev_b32_e32 v127, 2, v127
	ds_bpermute_b32 v127, v127, v126
	s_waitcnt lgkmcnt(0)
	v_add_f32_e32 v126, v126, v127
	v_xor_b32_e32 v127, 32, v197
	v_cmp_lt_i32_e32 vcc, v127, v128
	s_nop 1
	v_cndmask_b32_e32 v127, v197, v127, vcc
	v_lshlrev_b32_e32 v127, 2, v127
	ds_bpermute_b32 v127, v127, v126
	s_and_saveexec_b64 s[52:53], s[0:1]
	s_cbranch_execz .LBB0_1688
	v_lshlrev_b64 v[128:129], 6, v[138:139]
	v_readlane_b32 s26, v254, 43
	v_lshl_add_u64 v[128:129], s[30:31], 0, v[128:129]
	v_readlane_b32 s27, v254, 44
	v_lshl_add_u64 v[128:129], s[50:51], 2, v[128:129]
	s_mov_b32 s29, s27
	s_lshl_b32 s28, s65, 2
	v_writelane_b32 v254, s26, 43
	v_lshl_add_u64 v[128:129], v[128:129], 0, s[28:29]
	s_waitcnt lgkmcnt(0)
	v_add_f32_e32 v126, v126, v127
	v_writelane_b32 v254, s27, 44
	global_store_dword v[128:129], v126, off

.LBB0_1689:
	s_waitcnt lgkmcnt(0)
	global_load_dwordx4 v[126:129], v141, s[90:91] offset:64
	s_waitcnt vmcnt(0)
	v_pk_add_f32 v[124:125], v[124:125], v[128:129]
	v_pk_add_f32 v[122:123], v[122:123], v[126:127]
	global_store_dwordx4 v141, v[122:125], s[90:91] offset:64
	global_load_dwordx4 v[122:125], v141, s[90:91] offset:512
	s_waitcnt vmcnt(0)
	v_pk_add_f32 v[120:121], v[120:121], v[124:125]
	v_pk_add_f32 v[118:119], v[118:119], v[122:123]
	global_store_dwordx4 v141, v[118:121], s[90:91] offset:512
	global_load_dwordx4 v[118:121], v141, s[90:91] offset:576
	s_waitcnt vmcnt(0)
	v_pk_add_f32 v[116:117], v[116:117], v[120:121]
	v_pk_add_f32 v[114:115], v[114:115], v[118:119]
	global_store_dwordx4 v141, v[114:117], s[90:91] offset:576
.LBB0_1690:
	s_nop 1
	v_or_b32_e32 v116, 16, v138
	v_ashrrev_i32_e32 v117, 31, v116
	v_lshlrev_b64 v[114:115], 10, v[116:117]
	v_readlane_b32 s84, v254, 45
	v_lshl_add_u64 v[118:119], v[114:115], 0, v[136:137]
	v_readlane_b32 s90, v254, 51
	v_readlane_b32 s91, v254, 52
	s_and_b64 vcc, exec, s[38:39]
	v_readlane_b32 s85, v254, 46
	v_lshlrev_b32_e32 v115, 2, v118
	global_load_dwordx4 v[120:123], v115, s[90:91]
	v_readlane_b32 s86, v254, 47
	v_readlane_b32 s87, v254, 48
	v_readlane_b32 s88, v254, 49
	v_readlane_b32 s89, v254, 50
	s_waitcnt vmcnt(0)
	v_pk_add_f32 v[112:113], v[112:113], v[122:123]
	v_pk_add_f32 v[110:111], v[110:111], v[120:121]
	global_store_dwordx4 v115, v[110:113], s[90:91]
	s_cbranch_vccnz .LBB0_1729
	v_cvt_pk_bf16_f32 v120, v110, v111
	v_mul_f32_e32 v111, v111, v111
	v_cvt_pk_bf16_f32 v121, v112, v113
	v_lshlrev_b32_e32 v119, 1, v118
	v_fmac_f32_e32 v111, v110, v110
	v_mul_f32_e32 v110, v113, v113
	global_store_dwordx2 v119, v[120:121], s[4:5]
	v_fmac_f32_e32 v110, v112, v112
	v_add_f32_e32 v122, v111, v110
	global_load_dwordx4 v[110:113], v115, s[90:91] offset:64
	s_waitcnt vmcnt(0)
	v_pk_add_f32 v[112:113], v[108:109], v[112:113]
	v_pk_add_f32 v[110:111], v[106:107], v[110:111]
	global_store_dwordx4 v115, v[110:113], s[90:91] offset:64
	v_cvt_pk_bf16_f32 v120, v110, v111
	v_cvt_pk_bf16_f32 v121, v112, v113
	v_mul_f32_e32 v111, v111, v111
	v_fmac_f32_e32 v111, v110, v110
	v_mul_f32_e32 v110, v113, v113
	v_fmac_f32_e32 v110, v112, v112
	global_store_dwordx2 v119, v[120:121], s[4:5] offset:32
	v_add_f32_e32 v110, v111, v110
	v_add_f32_e32 v122, v122, v110
	global_load_dwordx4 v[110:113], v115, s[90:91] offset:512
	s_waitcnt vmcnt(0)
	v_pk_add_f32 v[112:113], v[104:105], v[112:113]
	v_pk_add_f32 v[110:111], v[102:103], v[110:111]
	global_store_dwordx4 v115, v[110:113], s[90:91] offset:512
	v_cvt_pk_bf16_f32 v120, v110, v111
	v_cvt_pk_bf16_f32 v121, v112, v113
	v_mul_f32_e32 v111, v111, v111
	v_fmac_f32_e32 v111, v110, v110
	v_mul_f32_e32 v110, v113, v113
	v_fmac_f32_e32 v110, v112, v112
	global_store_dwordx2 v119, v[120:121], s[4:5] offset:256
	v_add_f32_e32 v110, v111, v110
	v_add_f32_e32 v122, v122, v110
	global_load_dwordx4 v[110:113], v115, s[90:91] offset:576
	s_waitcnt vmcnt(0)
	v_pk_add_f32 v[112:113], v[100:101], v[112:113]
	v_pk_add_f32 v[110:111], v[98:99], v[110:111]
	global_store_dwordx4 v115, v[110:113], s[90:91] offset:576
	v_cvt_pk_bf16_f32 v120, v110, v111
	v_cvt_pk_bf16_f32 v121, v112, v113
	v_mul_f32_e32 v111, v111, v111
	v_fmac_f32_e32 v111, v110, v110
	v_mul_f32_e32 v110, v113, v113
	v_fmac_f32_e32 v110, v112, v112
	v_and_b32_e32 v112, 64, v197
	v_add_f32_e32 v110, v111, v110
	v_xor_b32_e32 v111, 16, v197
	v_add_u32_e32 v112, 64, v112
	v_cmp_lt_i32_e32 vcc, v111, v112
	v_add_f32_e32 v110, v122, v110
	global_store_dwordx2 v119, v[120:121], s[4:5] offset:288
	v_cndmask_b32_e32 v111, v197, v111, vcc
	v_lshlrev_b32_e32 v111, 2, v111
	ds_bpermute_b32 v111, v111, v110
	s_waitcnt lgkmcnt(0)
	v_add_f32_e32 v110, v110, v111
	v_xor_b32_e32 v111, 32, v197
	v_cmp_lt_i32_e32 vcc, v111, v112
	s_nop 1
	v_cndmask_b32_e32 v111, v197, v111, vcc
	v_lshlrev_b32_e32 v111, 2, v111
	ds_bpermute_b32 v111, v111, v110
	s_and_saveexec_b64 s[52:53], s[0:1]
	s_cbranch_execz .LBB0_1693
	v_lshlrev_b64 v[112:113], 6, v[116:117]
	v_readlane_b32 s26, v254, 43
	v_lshl_add_u64 v[112:113], s[30:31], 0, v[112:113]
	v_readlane_b32 s27, v254, 44
	v_lshl_add_u64 v[112:113], s[50:51], 2, v[112:113]
	s_mov_b32 s29, s27
	s_lshl_b32 s28, s65, 2
	v_writelane_b32 v254, s26, 43
	v_lshl_add_u64 v[112:113], v[112:113], 0, s[28:29]
	s_waitcnt lgkmcnt(0)
	v_add_f32_e32 v110, v110, v111
	v_writelane_b32 v254, s27, 44
	global_store_dword v[112:113], v110, off

.LBB0_1694:
	s_waitcnt lgkmcnt(0)
	global_load_dwordx4 v[110:113], v115, s[90:91] offset:64
	s_waitcnt vmcnt(0)
	v_pk_add_f32 v[108:109], v[108:109], v[112:113]
	v_pk_add_f32 v[106:107], v[106:107], v[110:111]
	global_store_dwordx4 v115, v[106:109], s[90:91] offset:64
	global_load_dwordx4 v[106:109], v115, s[90:91] offset:512
	s_waitcnt vmcnt(0)
	v_pk_add_f32 v[104:105], v[104:105], v[108:109]
	v_pk_add_f32 v[102:103], v[102:103], v[106:107]
	global_store_dwordx4 v115, v[102:105], s[90:91] offset:512
	global_load_dwordx4 v[102:105], v115, s[90:91] offset:576
	s_waitcnt vmcnt(0)
	v_pk_add_f32 v[100:101], v[100:101], v[104:105]
	v_pk_add_f32 v[98:99], v[98:99], v[102:103]
	global_store_dwordx4 v115, v[98:101], s[90:91] offset:576
.LBB0_1695:
	s_nop 1
	v_or_b32_e32 v100, 32, v138
	v_ashrrev_i32_e32 v101, 31, v100
	v_lshlrev_b64 v[98:99], 10, v[100:101]
	v_readlane_b32 s84, v254, 45
	v_lshl_add_u64 v[102:103], v[98:99], 0, v[136:137]
	v_readlane_b32 s90, v254, 51
	v_readlane_b32 s91, v254, 52
	s_and_b64 vcc, exec, s[38:39]
	v_readlane_b32 s85, v254, 46
	v_lshlrev_b32_e32 v99, 2, v102
	global_load_dwordx4 v[104:107], v99, s[90:91]
	v_readlane_b32 s86, v254, 47
	v_readlane_b32 s87, v254, 48
	v_readlane_b32 s88, v254, 49
	v_readlane_b32 s89, v254, 50
	s_waitcnt vmcnt(0)
	v_pk_add_f32 v[96:97], v[96:97], v[106:107]
	v_pk_add_f32 v[94:95], v[94:95], v[104:105]
	global_store_dwordx4 v99, v[94:97], s[90:91]
	s_cbranch_vccnz .LBB0_1730
	v_cvt_pk_bf16_f32 v104, v94, v95
	v_mul_f32_e32 v95, v95, v95
	v_cvt_pk_bf16_f32 v105, v96, v97
	v_lshlrev_b32_e32 v103, 1, v102
	v_fmac_f32_e32 v95, v94, v94
	v_mul_f32_e32 v94, v97, v97
	global_store_dwordx2 v103, v[104:105], s[4:5]
	v_fmac_f32_e32 v94, v96, v96
	v_add_f32_e32 v106, v95, v94
	global_load_dwordx4 v[94:97], v99, s[90:91] offset:64
	s_waitcnt vmcnt(0)
	v_pk_add_f32 v[96:97], v[92:93], v[96:97]
	v_pk_add_f32 v[94:95], v[90:91], v[94:95]
	global_store_dwordx4 v99, v[94:97], s[90:91] offset:64
	v_cvt_pk_bf16_f32 v104, v94, v95
	v_cvt_pk_bf16_f32 v105, v96, v97
	v_mul_f32_e32 v95, v95, v95
	v_fmac_f32_e32 v95, v94, v94
	v_mul_f32_e32 v94, v97, v97
	v_fmac_f32_e32 v94, v96, v96
	global_store_dwordx2 v103, v[104:105], s[4:5] offset:32
	v_add_f32_e32 v94, v95, v94
	v_add_f32_e32 v106, v106, v94
	global_load_dwordx4 v[94:97], v99, s[90:91] offset:512
	s_waitcnt vmcnt(0)
	v_pk_add_f32 v[96:97], v[88:89], v[96:97]
	v_pk_add_f32 v[94:95], v[86:87], v[94:95]
	global_store_dwordx4 v99, v[94:97], s[90:91] offset:512
	v_cvt_pk_bf16_f32 v104, v94, v95
	v_cvt_pk_bf16_f32 v105, v96, v97
	v_mul_f32_e32 v95, v95, v95
	v_fmac_f32_e32 v95, v94, v94
	v_mul_f32_e32 v94, v97, v97
	v_fmac_f32_e32 v94, v96, v96
	global_store_dwordx2 v103, v[104:105], s[4:5] offset:256
	v_add_f32_e32 v94, v95, v94
	v_add_f32_e32 v106, v106, v94
	global_load_dwordx4 v[94:97], v99, s[90:91] offset:576
	s_waitcnt vmcnt(0)
	v_pk_add_f32 v[96:97], v[84:85], v[96:97]
	v_pk_add_f32 v[94:95], v[82:83], v[94:95]
	global_store_dwordx4 v99, v[94:97], s[90:91] offset:576
	v_cvt_pk_bf16_f32 v104, v94, v95
	v_cvt_pk_bf16_f32 v105, v96, v97
	v_mul_f32_e32 v95, v95, v95
	v_fmac_f32_e32 v95, v94, v94
	v_mul_f32_e32 v94, v97, v97
	v_fmac_f32_e32 v94, v96, v96
	v_and_b32_e32 v96, 64, v197
	v_add_f32_e32 v94, v95, v94
	v_xor_b32_e32 v95, 16, v197
	v_add_u32_e32 v96, 64, v96
	v_cmp_lt_i32_e32 vcc, v95, v96
	v_add_f32_e32 v94, v106, v94
	global_store_dwordx2 v103, v[104:105], s[4:5] offset:288
	v_cndmask_b32_e32 v95, v197, v95, vcc
	v_lshlrev_b32_e32 v95, 2, v95
	ds_bpermute_b32 v95, v95, v94
	s_waitcnt lgkmcnt(0)
	v_add_f32_e32 v94, v94, v95
	v_xor_b32_e32 v95, 32, v197
	v_cmp_lt_i32_e32 vcc, v95, v96
	s_nop 1
	v_cndmask_b32_e32 v95, v197, v95, vcc
	v_lshlrev_b32_e32 v95, 2, v95
	ds_bpermute_b32 v95, v95, v94
	s_and_saveexec_b64 s[52:53], s[0:1]
	s_cbranch_execz .LBB0_1698
	v_lshlrev_b64 v[96:97], 6, v[100:101]
	v_readlane_b32 s26, v254, 43
	v_lshl_add_u64 v[96:97], s[30:31], 0, v[96:97]
	v_readlane_b32 s27, v254, 44
	v_lshl_add_u64 v[96:97], s[50:51], 2, v[96:97]
	s_mov_b32 s29, s27
	s_lshl_b32 s28, s65, 2
	v_writelane_b32 v254, s26, 43
	v_lshl_add_u64 v[96:97], v[96:97], 0, s[28:29]
	s_waitcnt lgkmcnt(0)
	v_add_f32_e32 v94, v94, v95
	v_writelane_b32 v254, s27, 44
	global_store_dword v[96:97], v94, off

.LBB0_1699:
	s_waitcnt lgkmcnt(0)
	global_load_dwordx4 v[94:97], v99, s[90:91] offset:64
	s_waitcnt vmcnt(0)
	v_pk_add_f32 v[92:93], v[92:93], v[96:97]
	v_pk_add_f32 v[90:91], v[90:91], v[94:95]
	global_store_dwordx4 v99, v[90:93], s[90:91] offset:64
	global_load_dwordx4 v[90:93], v99, s[90:91] offset:512
	s_waitcnt vmcnt(0)
	v_pk_add_f32 v[88:89], v[88:89], v[92:93]
	v_pk_add_f32 v[86:87], v[86:87], v[90:91]
	global_store_dwordx4 v99, v[86:89], s[90:91] offset:512
	global_load_dwordx4 v[86:89], v99, s[90:91] offset:576
	s_waitcnt vmcnt(0)
	v_pk_add_f32 v[84:85], v[84:85], v[88:89]
	v_pk_add_f32 v[82:83], v[82:83], v[86:87]
	global_store_dwordx4 v99, v[82:85], s[90:91] offset:576
.LBB0_1700:
	s_nop 1
	v_or_b32_e32 v84, 48, v138
	v_ashrrev_i32_e32 v85, 31, v84
	v_lshlrev_b64 v[82:83], 10, v[84:85]
	v_readlane_b32 s84, v254, 45
	v_lshl_add_u64 v[86:87], v[82:83], 0, v[136:137]
	v_readlane_b32 s90, v254, 51
	v_readlane_b32 s91, v254, 52
	s_and_b64 vcc, exec, s[38:39]
	v_readlane_b32 s85, v254, 46
	v_lshlrev_b32_e32 v83, 2, v86
	global_load_dwordx4 v[88:91], v83, s[90:91]
	v_readlane_b32 s86, v254, 47
	v_readlane_b32 s87, v254, 48
	v_readlane_b32 s88, v254, 49
	v_readlane_b32 s89, v254, 50
	s_waitcnt vmcnt(0)
	v_pk_add_f32 v[80:81], v[80:81], v[90:91]
	v_pk_add_f32 v[78:79], v[78:79], v[88:89]
	global_store_dwordx4 v83, v[78:81], s[90:91]
	s_cbranch_vccnz .LBB0_1731
	v_cvt_pk_bf16_f32 v88, v78, v79
	v_mul_f32_e32 v79, v79, v79
	v_cvt_pk_bf16_f32 v89, v80, v81
	v_lshlrev_b32_e32 v87, 1, v86
	v_fmac_f32_e32 v79, v78, v78
	v_mul_f32_e32 v78, v81, v81
	global_store_dwordx2 v87, v[88:89], s[4:5]
	v_fmac_f32_e32 v78, v80, v80
	v_add_f32_e32 v90, v79, v78
	global_load_dwordx4 v[78:81], v83, s[90:91] offset:64
	s_waitcnt vmcnt(0)
	v_pk_add_f32 v[80:81], v[76:77], v[80:81]
	v_pk_add_f32 v[78:79], v[74:75], v[78:79]
	global_store_dwordx4 v83, v[78:81], s[90:91] offset:64
	v_cvt_pk_bf16_f32 v88, v78, v79
	v_cvt_pk_bf16_f32 v89, v80, v81
	v_mul_f32_e32 v79, v79, v79
	v_fmac_f32_e32 v79, v78, v78
	v_mul_f32_e32 v78, v81, v81
	v_fmac_f32_e32 v78, v80, v80
	global_store_dwordx2 v87, v[88:89], s[4:5] offset:32
	v_add_f32_e32 v78, v79, v78
	v_add_f32_e32 v90, v90, v78
	global_load_dwordx4 v[78:81], v83, s[90:91] offset:512
	s_waitcnt vmcnt(0)
	v_pk_add_f32 v[80:81], v[72:73], v[80:81]
	v_pk_add_f32 v[78:79], v[70:71], v[78:79]
	global_store_dwordx4 v83, v[78:81], s[90:91] offset:512
	v_cvt_pk_bf16_f32 v88, v78, v79
	v_cvt_pk_bf16_f32 v89, v80, v81
	v_mul_f32_e32 v79, v79, v79
	v_fmac_f32_e32 v79, v78, v78
	v_mul_f32_e32 v78, v81, v81
	v_fmac_f32_e32 v78, v80, v80
	global_store_dwordx2 v87, v[88:89], s[4:5] offset:256
	v_add_f32_e32 v78, v79, v78
	v_add_f32_e32 v90, v90, v78
	global_load_dwordx4 v[78:81], v83, s[90:91] offset:576
	s_waitcnt vmcnt(0)
	v_pk_add_f32 v[80:81], v[68:69], v[80:81]
	v_pk_add_f32 v[78:79], v[66:67], v[78:79]
	global_store_dwordx4 v83, v[78:81], s[90:91] offset:576
	v_cvt_pk_bf16_f32 v88, v78, v79
	v_cvt_pk_bf16_f32 v89, v80, v81
	v_mul_f32_e32 v79, v79, v79
	v_fmac_f32_e32 v79, v78, v78
	v_mul_f32_e32 v78, v81, v81
	v_fmac_f32_e32 v78, v80, v80
	v_and_b32_e32 v80, 64, v197
	v_add_f32_e32 v78, v79, v78
	v_xor_b32_e32 v79, 16, v197
	v_add_u32_e32 v80, 64, v80
	v_cmp_lt_i32_e32 vcc, v79, v80
	v_add_f32_e32 v78, v90, v78
	global_store_dwordx2 v87, v[88:89], s[4:5] offset:288
	v_cndmask_b32_e32 v79, v197, v79, vcc
	v_lshlrev_b32_e32 v79, 2, v79
	ds_bpermute_b32 v79, v79, v78
	s_waitcnt lgkmcnt(0)
	v_add_f32_e32 v78, v78, v79
	v_xor_b32_e32 v79, 32, v197
	v_cmp_lt_i32_e32 vcc, v79, v80
	s_nop 1
	v_cndmask_b32_e32 v79, v197, v79, vcc
	v_lshlrev_b32_e32 v79, 2, v79
	ds_bpermute_b32 v79, v79, v78
	s_and_saveexec_b64 s[52:53], s[0:1]
	s_cbranch_execz .LBB0_1703
	v_lshlrev_b64 v[80:81], 6, v[84:85]
	v_readlane_b32 s26, v254, 43
	v_lshl_add_u64 v[80:81], s[30:31], 0, v[80:81]
	v_readlane_b32 s27, v254, 44
	v_lshl_add_u64 v[80:81], s[50:51], 2, v[80:81]
	s_mov_b32 s29, s27
	s_lshl_b32 s28, s65, 2
	v_writelane_b32 v254, s26, 43
	v_lshl_add_u64 v[80:81], v[80:81], 0, s[28:29]
	s_waitcnt lgkmcnt(0)
	v_add_f32_e32 v78, v78, v79
	v_writelane_b32 v254, s27, 44
	global_store_dword v[80:81], v78, off

.LBB0_1704:
	s_waitcnt lgkmcnt(0)
	global_load_dwordx4 v[78:81], v83, s[90:91] offset:64
	s_waitcnt vmcnt(0)
	v_pk_add_f32 v[76:77], v[76:77], v[80:81]
	v_pk_add_f32 v[74:75], v[74:75], v[78:79]
	global_store_dwordx4 v83, v[74:77], s[90:91] offset:64
	global_load_dwordx4 v[74:77], v83, s[90:91] offset:512
	s_waitcnt vmcnt(0)
	v_pk_add_f32 v[72:73], v[72:73], v[76:77]
	v_pk_add_f32 v[70:71], v[70:71], v[74:75]
	global_store_dwordx4 v83, v[70:73], s[90:91] offset:512
	global_load_dwordx4 v[70:73], v83, s[90:91] offset:576
	s_waitcnt vmcnt(0)
	v_pk_add_f32 v[68:69], v[68:69], v[72:73]
	v_pk_add_f32 v[66:67], v[66:67], v[70:71]
	global_store_dwordx4 v83, v[66:69], s[90:91] offset:576
.LBB0_1705:
	s_nop 1
	v_add_u32_e32 v68, 0x80, v138
	v_ashrrev_i32_e32 v69, 31, v68
	v_lshlrev_b64 v[66:67], 10, v[68:69]
	v_readlane_b32 s84, v254, 45
	v_lshl_add_u64 v[70:71], v[66:67], 0, v[136:137]
	v_readlane_b32 s90, v254, 51
	v_readlane_b32 s91, v254, 52
	s_and_b64 vcc, exec, s[38:39]
	v_readlane_b32 s85, v254, 46
	v_lshlrev_b32_e32 v67, 2, v70
	global_load_dwordx4 v[72:75], v67, s[90:91]
	v_readlane_b32 s86, v254, 47
	v_readlane_b32 s87, v254, 48
	v_readlane_b32 s88, v254, 49
	v_readlane_b32 s89, v254, 50
	s_waitcnt vmcnt(0)
	v_pk_add_f32 v[62:63], v[62:63], v[74:75]
	v_pk_add_f32 v[60:61], v[60:61], v[72:73]
	global_store_dwordx4 v67, v[60:63], s[90:91]
	s_cbranch_vccnz .LBB0_1732
	v_cvt_pk_bf16_f32 v72, v60, v61
	v_mul_f32_e32 v61, v61, v61
	v_cvt_pk_bf16_f32 v73, v62, v63
	v_lshlrev_b32_e32 v71, 1, v70
	v_fmac_f32_e32 v61, v60, v60
	v_mul_f32_e32 v60, v63, v63
	global_store_dwordx2 v71, v[72:73], s[4:5]
	v_fmac_f32_e32 v60, v62, v62
	v_add_f32_e32 v74, v61, v60
	global_load_dwordx4 v[60:63], v67, s[90:91] offset:64
	s_waitcnt vmcnt(0)
	v_pk_add_f32 v[62:63], v[58:59], v[62:63]
	v_pk_add_f32 v[60:61], v[56:57], v[60:61]
	global_store_dwordx4 v67, v[60:63], s[90:91] offset:64
	v_cvt_pk_bf16_f32 v72, v60, v61
	v_cvt_pk_bf16_f32 v73, v62, v63
	v_mul_f32_e32 v61, v61, v61
	v_fmac_f32_e32 v61, v60, v60
	v_mul_f32_e32 v60, v63, v63
	v_fmac_f32_e32 v60, v62, v62
	global_store_dwordx2 v71, v[72:73], s[4:5] offset:32
	v_add_f32_e32 v60, v61, v60
	v_add_f32_e32 v74, v74, v60
	global_load_dwordx4 v[60:63], v67, s[90:91] offset:512
	s_waitcnt vmcnt(0)
	v_pk_add_f32 v[62:63], v[54:55], v[62:63]
	v_pk_add_f32 v[60:61], v[52:53], v[60:61]
	global_store_dwordx4 v67, v[60:63], s[90:91] offset:512
	v_cvt_pk_bf16_f32 v72, v60, v61
	v_cvt_pk_bf16_f32 v73, v62, v63
	v_mul_f32_e32 v61, v61, v61
	v_fmac_f32_e32 v61, v60, v60
	v_mul_f32_e32 v60, v63, v63
	v_fmac_f32_e32 v60, v62, v62
	global_store_dwordx2 v71, v[72:73], s[4:5] offset:256
	v_add_f32_e32 v60, v61, v60
	v_add_f32_e32 v74, v74, v60
	global_load_dwordx4 v[60:63], v67, s[90:91] offset:576
	s_waitcnt vmcnt(0)
	v_pk_add_f32 v[62:63], v[50:51], v[62:63]
	v_pk_add_f32 v[60:61], v[48:49], v[60:61]
	global_store_dwordx4 v67, v[60:63], s[90:91] offset:576
	v_cvt_pk_bf16_f32 v72, v60, v61
	v_cvt_pk_bf16_f32 v73, v62, v63
	v_mul_f32_e32 v61, v61, v61
	v_fmac_f32_e32 v61, v60, v60
	v_mul_f32_e32 v60, v63, v63
	v_fmac_f32_e32 v60, v62, v62
	v_and_b32_e32 v62, 64, v197
	v_add_f32_e32 v60, v61, v60
	v_xor_b32_e32 v61, 16, v197
	v_add_u32_e32 v62, 64, v62
	v_cmp_lt_i32_e32 vcc, v61, v62
	v_add_f32_e32 v60, v74, v60
	global_store_dwordx2 v71, v[72:73], s[4:5] offset:288
	v_cndmask_b32_e32 v61, v197, v61, vcc
	v_lshlrev_b32_e32 v61, 2, v61
	ds_bpermute_b32 v61, v61, v60
	s_waitcnt lgkmcnt(0)
	v_add_f32_e32 v60, v60, v61
	v_xor_b32_e32 v61, 32, v197
	v_cmp_lt_i32_e32 vcc, v61, v62
	s_nop 1
	v_cndmask_b32_e32 v61, v197, v61, vcc
	v_lshlrev_b32_e32 v61, 2, v61
	ds_bpermute_b32 v61, v61, v60
	s_and_saveexec_b64 s[52:53], s[0:1]
	s_cbranch_execz .LBB0_1708
	v_lshlrev_b64 v[62:63], 6, v[68:69]
	v_readlane_b32 s26, v254, 43
	v_lshl_add_u64 v[62:63], s[30:31], 0, v[62:63]
	v_readlane_b32 s27, v254, 44
	v_lshl_add_u64 v[62:63], s[50:51], 2, v[62:63]
	s_mov_b32 s29, s27
	s_lshl_b32 s28, s65, 2
	v_writelane_b32 v254, s26, 43
	v_lshl_add_u64 v[62:63], v[62:63], 0, s[28:29]
	s_waitcnt lgkmcnt(0)
	v_add_f32_e32 v60, v60, v61
	v_writelane_b32 v254, s27, 44
	global_store_dword v[62:63], v60, off

.LBB0_1709:
	s_waitcnt lgkmcnt(0)
	global_load_dwordx4 v[60:63], v67, s[90:91] offset:64
	s_waitcnt vmcnt(0)
	v_pk_add_f32 v[58:59], v[58:59], v[62:63]
	v_pk_add_f32 v[56:57], v[56:57], v[60:61]
	global_store_dwordx4 v67, v[56:59], s[90:91] offset:64
	global_load_dwordx4 v[56:59], v67, s[90:91] offset:512
	s_waitcnt vmcnt(0)
	v_pk_add_f32 v[54:55], v[54:55], v[58:59]
	v_pk_add_f32 v[52:53], v[52:53], v[56:57]
	global_store_dwordx4 v67, v[52:55], s[90:91] offset:512
	global_load_dwordx4 v[52:55], v67, s[90:91] offset:576
	s_waitcnt vmcnt(0)
	v_pk_add_f32 v[50:51], v[50:51], v[54:55]
	v_pk_add_f32 v[48:49], v[48:49], v[52:53]
	global_store_dwordx4 v67, v[48:51], s[90:91] offset:576
.LBB0_1710:
	s_nop 1
	v_add_u32_e32 v50, 0x90, v138
	v_ashrrev_i32_e32 v51, 31, v50
	v_lshlrev_b64 v[48:49], 10, v[50:51]
	v_readlane_b32 s84, v254, 45
	v_lshl_add_u64 v[52:53], v[48:49], 0, v[136:137]
	v_readlane_b32 s90, v254, 51
	v_readlane_b32 s91, v254, 52
	s_and_b64 vcc, exec, s[38:39]
	v_readlane_b32 s85, v254, 46
	v_lshlrev_b32_e32 v49, 2, v52
	global_load_dwordx4 v[54:57], v49, s[90:91]
	v_readlane_b32 s86, v254, 47
	v_readlane_b32 s87, v254, 48
	v_readlane_b32 s88, v254, 49
	v_readlane_b32 s89, v254, 50
	s_waitcnt vmcnt(0)
	v_pk_add_f32 v[46:47], v[46:47], v[56:57]
	v_pk_add_f32 v[44:45], v[44:45], v[54:55]
	global_store_dwordx4 v49, v[44:47], s[90:91]
	s_cbranch_vccnz .LBB0_1733
	v_cvt_pk_bf16_f32 v54, v44, v45
	v_mul_f32_e32 v45, v45, v45
	v_cvt_pk_bf16_f32 v55, v46, v47
	v_lshlrev_b32_e32 v53, 1, v52
	v_fmac_f32_e32 v45, v44, v44
	v_mul_f32_e32 v44, v47, v47
	global_store_dwordx2 v53, v[54:55], s[4:5]
	v_fmac_f32_e32 v44, v46, v46
	v_add_f32_e32 v56, v45, v44
	global_load_dwordx4 v[44:47], v49, s[90:91] offset:64
	s_waitcnt vmcnt(0)
	v_pk_add_f32 v[46:47], v[42:43], v[46:47]
	v_pk_add_f32 v[44:45], v[40:41], v[44:45]
	global_store_dwordx4 v49, v[44:47], s[90:91] offset:64
	v_cvt_pk_bf16_f32 v54, v44, v45
	v_cvt_pk_bf16_f32 v55, v46, v47
	v_mul_f32_e32 v45, v45, v45
	v_fmac_f32_e32 v45, v44, v44
	v_mul_f32_e32 v44, v47, v47
	v_fmac_f32_e32 v44, v46, v46
	global_store_dwordx2 v53, v[54:55], s[4:5] offset:32
	v_add_f32_e32 v44, v45, v44
	v_add_f32_e32 v56, v56, v44
	global_load_dwordx4 v[44:47], v49, s[90:91] offset:512
	s_waitcnt vmcnt(0)
	v_pk_add_f32 v[46:47], v[38:39], v[46:47]
	v_pk_add_f32 v[44:45], v[36:37], v[44:45]
	global_store_dwordx4 v49, v[44:47], s[90:91] offset:512
	v_cvt_pk_bf16_f32 v54, v44, v45
	v_cvt_pk_bf16_f32 v55, v46, v47
	v_mul_f32_e32 v45, v45, v45
	v_fmac_f32_e32 v45, v44, v44
	v_mul_f32_e32 v44, v47, v47
	v_fmac_f32_e32 v44, v46, v46
	global_store_dwordx2 v53, v[54:55], s[4:5] offset:256
	v_add_f32_e32 v44, v45, v44
	v_add_f32_e32 v56, v56, v44
	global_load_dwordx4 v[44:47], v49, s[90:91] offset:576
	s_waitcnt vmcnt(0)
	v_pk_add_f32 v[46:47], v[34:35], v[46:47]
	v_pk_add_f32 v[44:45], v[32:33], v[44:45]
	global_store_dwordx4 v49, v[44:47], s[90:91] offset:576
	v_cvt_pk_bf16_f32 v54, v44, v45
	v_cvt_pk_bf16_f32 v55, v46, v47
	v_mul_f32_e32 v45, v45, v45
	v_fmac_f32_e32 v45, v44, v44
	v_mul_f32_e32 v44, v47, v47
	v_fmac_f32_e32 v44, v46, v46
	v_and_b32_e32 v46, 64, v197
	v_add_f32_e32 v44, v45, v44
	v_xor_b32_e32 v45, 16, v197
	v_add_u32_e32 v46, 64, v46
	v_cmp_lt_i32_e32 vcc, v45, v46
	v_add_f32_e32 v44, v56, v44
	global_store_dwordx2 v53, v[54:55], s[4:5] offset:288
	v_cndmask_b32_e32 v45, v197, v45, vcc
	v_lshlrev_b32_e32 v45, 2, v45
	ds_bpermute_b32 v45, v45, v44
	s_waitcnt lgkmcnt(0)
	v_add_f32_e32 v44, v44, v45
	v_xor_b32_e32 v45, 32, v197
	v_cmp_lt_i32_e32 vcc, v45, v46
	s_nop 1
	v_cndmask_b32_e32 v45, v197, v45, vcc
	v_lshlrev_b32_e32 v45, 2, v45
	ds_bpermute_b32 v45, v45, v44
	s_and_saveexec_b64 s[52:53], s[0:1]
	s_cbranch_execz .LBB0_1713
	v_lshlrev_b64 v[46:47], 6, v[50:51]
	v_readlane_b32 s26, v254, 43
	v_lshl_add_u64 v[46:47], s[30:31], 0, v[46:47]
	v_readlane_b32 s27, v254, 44
	v_lshl_add_u64 v[46:47], s[50:51], 2, v[46:47]
	s_mov_b32 s29, s27
	s_lshl_b32 s28, s65, 2
	v_writelane_b32 v254, s26, 43
	v_lshl_add_u64 v[46:47], v[46:47], 0, s[28:29]
	s_waitcnt lgkmcnt(0)
	v_add_f32_e32 v44, v44, v45
	v_writelane_b32 v254, s27, 44
	global_store_dword v[46:47], v44, off

.LBB0_1714:
	s_waitcnt lgkmcnt(0)
	global_load_dwordx4 v[44:47], v49, s[90:91] offset:64
	s_waitcnt vmcnt(0)
	v_pk_add_f32 v[42:43], v[42:43], v[46:47]
	v_pk_add_f32 v[40:41], v[40:41], v[44:45]
	global_store_dwordx4 v49, v[40:43], s[90:91] offset:64
	global_load_dwordx4 v[40:43], v49, s[90:91] offset:512
	s_waitcnt vmcnt(0)
	v_pk_add_f32 v[38:39], v[38:39], v[42:43]
	v_pk_add_f32 v[36:37], v[36:37], v[40:41]
	global_store_dwordx4 v49, v[36:39], s[90:91] offset:512
	global_load_dwordx4 v[36:39], v49, s[90:91] offset:576
	s_waitcnt vmcnt(0)
	v_pk_add_f32 v[34:35], v[34:35], v[38:39]
	v_pk_add_f32 v[32:33], v[32:33], v[36:37]
	global_store_dwordx4 v49, v[32:35], s[90:91] offset:576
.LBB0_1715:
	s_nop 1
	v_add_u32_e32 v34, 0xa0, v138
	v_ashrrev_i32_e32 v35, 31, v34
	v_lshlrev_b64 v[32:33], 10, v[34:35]
	v_readlane_b32 s84, v254, 45
	v_lshl_add_u64 v[36:37], v[32:33], 0, v[136:137]
	v_readlane_b32 s90, v254, 51
	v_readlane_b32 s91, v254, 52
	s_and_b64 vcc, exec, s[38:39]
	v_readlane_b32 s85, v254, 46
	v_lshlrev_b32_e32 v33, 2, v36
	global_load_dwordx4 v[38:41], v33, s[90:91]
	v_readlane_b32 s86, v254, 47
	v_readlane_b32 s87, v254, 48
	v_readlane_b32 s88, v254, 49
	v_readlane_b32 s89, v254, 50
	s_waitcnt vmcnt(0)
	v_pk_add_f32 v[30:31], v[30:31], v[40:41]
	v_pk_add_f32 v[28:29], v[28:29], v[38:39]
	global_store_dwordx4 v33, v[28:31], s[90:91]
	s_cbranch_vccnz .LBB0_1734
	v_cvt_pk_bf16_f32 v38, v28, v29
	v_mul_f32_e32 v29, v29, v29
	v_cvt_pk_bf16_f32 v39, v30, v31
	v_lshlrev_b32_e32 v37, 1, v36
	v_fmac_f32_e32 v29, v28, v28
	v_mul_f32_e32 v28, v31, v31
	global_store_dwordx2 v37, v[38:39], s[4:5]
	v_fmac_f32_e32 v28, v30, v30
	v_add_f32_e32 v40, v29, v28
	global_load_dwordx4 v[28:31], v33, s[90:91] offset:64
	s_waitcnt vmcnt(0)
	v_pk_add_f32 v[30:31], v[26:27], v[30:31]
	v_pk_add_f32 v[28:29], v[24:25], v[28:29]
	global_store_dwordx4 v33, v[28:31], s[90:91] offset:64
	v_cvt_pk_bf16_f32 v38, v28, v29
	v_cvt_pk_bf16_f32 v39, v30, v31
	v_mul_f32_e32 v29, v29, v29
	v_fmac_f32_e32 v29, v28, v28
	v_mul_f32_e32 v28, v31, v31
	v_fmac_f32_e32 v28, v30, v30
	global_store_dwordx2 v37, v[38:39], s[4:5] offset:32
	v_add_f32_e32 v28, v29, v28
	v_add_f32_e32 v40, v40, v28
	global_load_dwordx4 v[28:31], v33, s[90:91] offset:512
	s_waitcnt vmcnt(0)
	v_pk_add_f32 v[30:31], v[22:23], v[30:31]
	v_pk_add_f32 v[28:29], v[20:21], v[28:29]
	global_store_dwordx4 v33, v[28:31], s[90:91] offset:512
	v_cvt_pk_bf16_f32 v38, v28, v29
	v_cvt_pk_bf16_f32 v39, v30, v31
	v_mul_f32_e32 v29, v29, v29
	v_fmac_f32_e32 v29, v28, v28
	v_mul_f32_e32 v28, v31, v31
	v_fmac_f32_e32 v28, v30, v30
	global_store_dwordx2 v37, v[38:39], s[4:5] offset:256
	v_add_f32_e32 v28, v29, v28
	v_add_f32_e32 v40, v40, v28
	global_load_dwordx4 v[28:31], v33, s[90:91] offset:576
	s_waitcnt vmcnt(0)
	v_pk_add_f32 v[30:31], v[18:19], v[30:31]
	v_pk_add_f32 v[28:29], v[16:17], v[28:29]
	global_store_dwordx4 v33, v[28:31], s[90:91] offset:576
	v_cvt_pk_bf16_f32 v38, v28, v29
	v_cvt_pk_bf16_f32 v39, v30, v31
	v_mul_f32_e32 v29, v29, v29
	v_fmac_f32_e32 v29, v28, v28
	v_mul_f32_e32 v28, v31, v31
	v_fmac_f32_e32 v28, v30, v30
	v_and_b32_e32 v30, 64, v197
	v_add_f32_e32 v28, v29, v28
	v_xor_b32_e32 v29, 16, v197
	v_add_u32_e32 v30, 64, v30
	v_cmp_lt_i32_e32 vcc, v29, v30
	v_add_f32_e32 v28, v40, v28
	global_store_dwordx2 v37, v[38:39], s[4:5] offset:288
	v_cndmask_b32_e32 v29, v197, v29, vcc
	v_lshlrev_b32_e32 v29, 2, v29
	ds_bpermute_b32 v29, v29, v28
	s_waitcnt lgkmcnt(0)
	v_add_f32_e32 v28, v28, v29
	v_xor_b32_e32 v29, 32, v197
	v_cmp_lt_i32_e32 vcc, v29, v30
	s_nop 1
	v_cndmask_b32_e32 v29, v197, v29, vcc
	v_lshlrev_b32_e32 v29, 2, v29
	ds_bpermute_b32 v29, v29, v28
	s_and_saveexec_b64 s[52:53], s[0:1]
	s_cbranch_execz .LBB0_1718
	v_lshlrev_b64 v[30:31], 6, v[34:35]
	v_readlane_b32 s26, v254, 43
	v_lshl_add_u64 v[30:31], s[30:31], 0, v[30:31]
	v_readlane_b32 s27, v254, 44
	v_lshl_add_u64 v[30:31], s[50:51], 2, v[30:31]
	s_mov_b32 s29, s27
	s_lshl_b32 s28, s65, 2
	v_writelane_b32 v254, s26, 43
	v_lshl_add_u64 v[30:31], v[30:31], 0, s[28:29]
	s_waitcnt lgkmcnt(0)
	v_add_f32_e32 v28, v28, v29
	v_writelane_b32 v254, s27, 44
	global_store_dword v[30:31], v28, off

.LBB0_1719:
	s_waitcnt lgkmcnt(0)
	global_load_dwordx4 v[28:31], v33, s[90:91] offset:64
	s_waitcnt vmcnt(0)
	v_pk_add_f32 v[26:27], v[26:27], v[30:31]
	v_pk_add_f32 v[24:25], v[24:25], v[28:29]
	global_store_dwordx4 v33, v[24:27], s[90:91] offset:64
	global_load_dwordx4 v[24:27], v33, s[90:91] offset:512
	s_waitcnt vmcnt(0)
	v_pk_add_f32 v[22:23], v[22:23], v[26:27]
	v_pk_add_f32 v[20:21], v[20:21], v[24:25]
	global_store_dwordx4 v33, v[20:23], s[90:91] offset:512
	global_load_dwordx4 v[20:23], v33, s[90:91] offset:576
	s_waitcnt vmcnt(0)
	v_pk_add_f32 v[18:19], v[18:19], v[22:23]
	v_pk_add_f32 v[16:17], v[16:17], v[20:21]
	global_store_dwordx4 v33, v[16:19], s[90:91] offset:576
.LBB0_1720:
	s_nop 1
	v_add_u32_e32 v18, 0xb0, v138
	v_ashrrev_i32_e32 v19, 31, v18
	v_lshlrev_b64 v[16:17], 10, v[18:19]
	v_readlane_b32 s84, v254, 45
	v_lshl_add_u64 v[20:21], v[16:17], 0, v[136:137]
	v_readlane_b32 s90, v254, 51
	v_readlane_b32 s91, v254, 52
	s_and_b64 vcc, exec, s[38:39]
	v_readlane_b32 s85, v254, 46
	v_lshlrev_b32_e32 v17, 2, v20
	global_load_dwordx4 v[22:25], v17, s[90:91]
	v_readlane_b32 s86, v254, 47
	v_readlane_b32 s87, v254, 48
	v_readlane_b32 s88, v254, 49
	v_readlane_b32 s89, v254, 50
	s_waitcnt vmcnt(0)
	v_pk_add_f32 v[14:15], v[14:15], v[24:25]
	v_pk_add_f32 v[12:13], v[12:13], v[22:23]
	global_store_dwordx4 v17, v[12:15], s[90:91]
	s_cbranch_vccnz .LBB0_1735
	v_cvt_pk_bf16_f32 v22, v12, v13
	v_mul_f32_e32 v13, v13, v13
	v_cvt_pk_bf16_f32 v23, v14, v15
	v_lshlrev_b32_e32 v21, 1, v20
	v_fmac_f32_e32 v13, v12, v12
	v_mul_f32_e32 v12, v15, v15
	global_store_dwordx2 v21, v[22:23], s[4:5]
	v_fmac_f32_e32 v12, v14, v14
	v_add_f32_e32 v24, v13, v12
	global_load_dwordx4 v[12:15], v17, s[90:91] offset:64
	s_waitcnt vmcnt(0)
	v_pk_add_f32 v[14:15], v[10:11], v[14:15]
	v_pk_add_f32 v[12:13], v[8:9], v[12:13]
	global_store_dwordx4 v17, v[12:15], s[90:91] offset:64
	v_cvt_pk_bf16_f32 v22, v12, v13
	v_cvt_pk_bf16_f32 v23, v14, v15
	v_mul_f32_e32 v13, v13, v13
	v_fmac_f32_e32 v13, v12, v12
	v_mul_f32_e32 v12, v15, v15
	v_fmac_f32_e32 v12, v14, v14
	global_store_dwordx2 v21, v[22:23], s[4:5] offset:32
	v_add_f32_e32 v12, v13, v12
	v_add_f32_e32 v24, v24, v12
	global_load_dwordx4 v[12:15], v17, s[90:91] offset:512
	s_waitcnt vmcnt(0)
	v_pk_add_f32 v[14:15], v[6:7], v[14:15]
	v_pk_add_f32 v[12:13], v[4:5], v[12:13]
	global_store_dwordx4 v17, v[12:15], s[90:91] offset:512
	v_cvt_pk_bf16_f32 v22, v12, v13
	v_cvt_pk_bf16_f32 v23, v14, v15
	v_mul_f32_e32 v13, v13, v13
	v_fmac_f32_e32 v13, v12, v12
	v_mul_f32_e32 v12, v15, v15
	v_fmac_f32_e32 v12, v14, v14
	global_store_dwordx2 v21, v[22:23], s[4:5] offset:256
	v_add_f32_e32 v12, v13, v12
	v_add_f32_e32 v24, v24, v12
	global_load_dwordx4 v[12:15], v17, s[90:91] offset:576
	s_waitcnt vmcnt(0)
	v_pk_add_f32 v[14:15], v[2:3], v[14:15]
	v_pk_add_f32 v[12:13], v[0:1], v[12:13]
	global_store_dwordx4 v17, v[12:15], s[90:91] offset:576
	v_cvt_pk_bf16_f32 v22, v12, v13
	v_cvt_pk_bf16_f32 v23, v14, v15
	v_mul_f32_e32 v13, v13, v13
	v_fmac_f32_e32 v13, v12, v12
	v_mul_f32_e32 v12, v15, v15
	v_fmac_f32_e32 v12, v14, v14
	v_and_b32_e32 v14, 64, v197
	v_add_f32_e32 v12, v13, v12
	v_xor_b32_e32 v13, 16, v197
	v_add_u32_e32 v14, 64, v14
	v_cmp_lt_i32_e32 vcc, v13, v14
	v_add_f32_e32 v12, v24, v12
	global_store_dwordx2 v21, v[22:23], s[4:5] offset:288
	v_cndmask_b32_e32 v13, v197, v13, vcc
	v_lshlrev_b32_e32 v13, 2, v13
	ds_bpermute_b32 v13, v13, v12
	s_waitcnt lgkmcnt(0)
	v_add_f32_e32 v12, v12, v13
	v_xor_b32_e32 v13, 32, v197
	v_cmp_lt_i32_e32 vcc, v13, v14
	s_nop 1
	v_cndmask_b32_e32 v13, v197, v13, vcc
	v_lshlrev_b32_e32 v13, 2, v13
	ds_bpermute_b32 v13, v13, v12
	s_and_saveexec_b64 s[38:39], s[0:1]
	s_cbranch_execz .LBB0_1723
	v_lshlrev_b64 v[14:15], 6, v[18:19]
	v_readlane_b32 s26, v254, 43
	v_lshl_add_u64 v[14:15], s[30:31], 0, v[14:15]
	v_readlane_b32 s27, v254, 44
	v_lshl_add_u64 v[14:15], s[50:51], 2, v[14:15]
	s_mov_b32 s29, s27
	s_lshl_b32 s28, s65, 2
	v_writelane_b32 v254, s26, 43
	v_lshl_add_u64 v[14:15], v[14:15], 0, s[28:29]
	s_waitcnt lgkmcnt(0)
	v_add_f32_e32 v12, v12, v13
	v_writelane_b32 v254, s27, 44
	global_store_dword v[14:15], v12, off

.LBB0_1724:
	s_waitcnt lgkmcnt(0)
	global_load_dwordx4 v[12:15], v17, s[90:91] offset:64
	s_waitcnt vmcnt(0)
	v_pk_add_f32 v[10:11], v[10:11], v[14:15]
	v_pk_add_f32 v[8:9], v[8:9], v[12:13]
	global_store_dwordx4 v17, v[8:11], s[90:91] offset:64
	global_load_dwordx4 v[8:11], v17, s[90:91] offset:512
	s_waitcnt vmcnt(0)
	v_pk_add_f32 v[6:7], v[6:7], v[10:11]
	v_pk_add_f32 v[4:5], v[4:5], v[8:9]
	global_store_dwordx4 v17, v[4:7], s[90:91] offset:512
	global_load_dwordx4 v[4:7], v17, s[90:91] offset:576
	s_waitcnt vmcnt(0)
	v_pk_add_f32 v[2:3], v[2:3], v[6:7]
	v_pk_add_f32 v[0:1], v[0:1], v[4:5]
	global_store_dwordx4 v17, v[0:3], s[90:91] offset:576
